# merge phase: 11 blocks of the running merged tile in registers + 3 in static LDS (DMA address pairs recomputed from SGPR bases, phase constants set after the loop)
# speedup vs baseline: 1.0381x; 1.0061x over previous
.LBB0_1018:
	s_ashr_i32 s15, s14, 31
	s_ashr_i32 s13, s12, 31
	s_lshl_b64 s[16:17], s[14:15], 19
	s_lshl_b64 s[18:19], s[12:13], 9
	s_add_u32 s13, s34, s16
	s_addc_u32 s15, s35, s17
	s_add_u32 s16, s13, s18
	s_addc_u32 s17, s15, s19
	s_and_b64 s[18:19], s[2:3], exec
	s_cselect_b32 s29, s17, s23
	s_cselect_b32 s28, s16, s22
	s_lshl_b32 s13, s12, 2
	s_add_i32 s18, s13, s51
	s_ashr_i32 s19, s18, 31
	s_lshl_b64 s[18:19], s[18:19], 17
	s_add_u32 s18, s36, s18
	s_addc_u32 s19, s37, s19
	s_and_b64 s[26:27], s[2:3], exec
	s_cselect_b32 s27, s19, s25
	s_cselect_b32 s26, s18, s24
	s_add_i32 s15, 0, 0x10000
	s_add_i32 s21, 0, 0x14000
	v_add_u32_e32 v253, s15, v174
	v_add_u32_e32 v252, s21, v174
	ds_read_b128 v[168:171], v253
	ds_read_b128 v[176:179], v253 offset:1024
	ds_read_b128 v[240:243], v253 offset:2048
	ds_read_b128 v[128:131], v253 offset:3072
	ds_read_b128 v[132:135], v252
	ds_read_b128 v[136:139], v252 offset:1024
	ds_read_b128 v[140:143], v252 offset:2048
	ds_read_b128 v[144:147], v252 offset:3072
	s_add_u32 s52, s22, 0x40080
	s_addc_u32 s53, s23, 0
	s_add_i32 s55, s39, 0xc000
	s_waitcnt vmcnt(0)
	v_lshl_add_u64 v[234:235], s[52:53], 0, v[160:161]
	s_mov_b32 m0, s55
	s_add_i32 s13, s39, 0xe000
	ds_read_b128 v[148:151], v175
	ds_read_b128 v[152:155], v175 offset:1024
	ds_read_b128 v[156:159], v175 offset:2048
	ds_read_b128 v[180:183], v175 offset:3072
	ds_read_b128 v[184:187], v175 offset:4096
	ds_read_b128 v[188:191], v175 offset:5120
	ds_read_b128 v[192:195], v175 offset:6144
	ds_read_b128 v[196:199], v175 offset:7168
	global_load_lds_dwordx4 v[234:235], off
	v_lshl_add_u64 v[234:235], s[52:53], 0, v[162:163]
	s_mov_b32 m0, s13
	s_nop 0
	global_load_lds_dwordx4 v[234:235], off
	s_waitcnt vmcnt(8)
	s_waitcnt lgkmcnt(0)
	s_barrier
	s_setprio 1
	s_waitcnt lgkmcnt(0)
	v_mfma_f32_16x16x32_bf16 v[0:3], v[168:171], v[148:151], 0
	v_mfma_f32_16x16x32_bf16 v[4:7], v[240:243], v[148:151], 0
	v_mfma_f32_16x16x32_bf16 v[16:19], v[168:171], v[156:159], 0
	v_mfma_f32_16x16x32_bf16 v[20:23], v[240:243], v[156:159], 0
	v_mfma_f32_16x16x32_bf16 v[32:35], v[168:171], v[184:187], 0
	v_mfma_f32_16x16x32_bf16 v[36:39], v[240:243], v[184:187], 0
	v_mfma_f32_16x16x32_bf16 v[48:51], v[168:171], v[192:195], 0
	v_mfma_f32_16x16x32_bf16 v[52:55], v[240:243], v[192:195], 0
	v_mfma_f32_16x16x32_bf16 v[0:3], v[176:179], v[152:155], v[0:3]
	v_mfma_f32_16x16x32_bf16 v[4:7], v[128:131], v[152:155], v[4:7]
	v_mfma_f32_16x16x32_bf16 v[16:19], v[176:179], v[180:183], v[16:19]
	v_mfma_f32_16x16x32_bf16 v[20:23], v[128:131], v[180:183], v[20:23]
	v_mfma_f32_16x16x32_bf16 v[32:35], v[176:179], v[188:191], v[32:35]
	v_mfma_f32_16x16x32_bf16 v[36:39], v[128:131], v[188:191], v[36:39]
	v_mfma_f32_16x16x32_bf16 v[48:51], v[176:179], v[196:199], v[48:51]
	v_mfma_f32_16x16x32_bf16 v[52:55], v[128:131], v[196:199], v[52:55]
	s_setprio 0
	s_setprio 1
	v_mfma_f32_16x16x32_bf16 v[8:11], v[132:135], v[148:151], 0
	v_mfma_f32_16x16x32_bf16 v[12:15], v[140:143], v[148:151], 0
	v_mfma_f32_16x16x32_bf16 v[8:11], v[136:139], v[152:155], v[8:11]
	v_mfma_f32_16x16x32_bf16 v[12:15], v[144:147], v[152:155], v[12:15]
	v_mfma_f32_16x16x32_bf16 v[24:27], v[132:135], v[156:159], 0
	v_mfma_f32_16x16x32_bf16 v[28:31], v[140:143], v[156:159], 0
	v_mfma_f32_16x16x32_bf16 v[24:27], v[136:139], v[180:183], v[24:27]
	v_mfma_f32_16x16x32_bf16 v[28:31], v[144:147], v[180:183], v[28:31]
	v_mfma_f32_16x16x32_bf16 v[40:43], v[132:135], v[184:187], 0
	v_mfma_f32_16x16x32_bf16 v[44:47], v[140:143], v[184:187], 0
	v_mfma_f32_16x16x32_bf16 v[40:43], v[136:139], v[188:191], v[40:43]
	v_mfma_f32_16x16x32_bf16 v[44:47], v[144:147], v[188:191], v[44:47]
	v_mfma_f32_16x16x32_bf16 v[56:59], v[132:135], v[192:195], 0
	v_mfma_f32_16x16x32_bf16 v[60:63], v[140:143], v[192:195], 0
	v_mfma_f32_16x16x32_bf16 v[56:59], v[136:139], v[196:199], v[56:59]
	v_mfma_f32_16x16x32_bf16 v[60:63], v[144:147], v[196:199], v[60:63]
	s_setprio 0
	s_barrier
	s_add_i32 s53, s15, s38
	v_lshl_add_u64 v[234:235], s[24:25], 0, v[232:233]
	s_mov_b64 s[58:59], 0x100
	s_add_i32 s15, s53, 0x2000
	v_lshl_add_u64 v[166:167], v[234:235], 0, s[58:59]
	s_mov_b32 m0, s53
	v_lshl_add_u64 v[234:235], s[24:25], 0, v[164:165]
	s_add_u32 s56, s24, 0x10100
	ds_read_b128 v[148:151], v175 offset:16384
	ds_read_b128 v[152:155], v175 offset:17408
	ds_read_b128 v[156:159], v175 offset:18432
	ds_read_b128 v[180:183], v175 offset:19456
	ds_read_b128 v[184:187], v175 offset:20480
	ds_read_b128 v[188:191], v175 offset:21504
	ds_read_b128 v[192:195], v175 offset:22528
	ds_read_b128 v[196:199], v175 offset:23552
	global_load_lds_dwordx4 v[166:167], off
	v_lshl_add_u64 v[166:167], v[234:235], 0, s[58:59]
	s_mov_b32 m0, s15
	s_addc_u32 s57, s25, 0
	s_add_i32 s21, s21, s38
	global_load_lds_dwordx4 v[166:167], off
	v_lshl_add_u64 v[234:235], s[56:57], 0, v[232:233]
	s_mov_b32 m0, s21
	s_add_i32 s52, s21, 0x2000
	global_load_lds_dwordx4 v[234:235], off
	v_lshl_add_u64 v[234:235], s[56:57], 0, v[164:165]
	s_mov_b32 m0, s52
	v_lshl_add_u64 v[166:167], s[22:23], 0, v[160:161]
	global_load_lds_dwordx4 v[234:235], off
	v_lshl_add_u64 v[234:235], v[166:167], 0, s[58:59]
	s_mov_b32 m0, s39
	v_lshl_add_u64 v[166:167], s[22:23], 0, v[162:163]
	global_load_lds_dwordx4 v[234:235], off
	v_lshl_add_u64 v[234:235], v[166:167], 0, s[58:59]
	s_mov_b32 m0, s40
	s_nop 0
	global_load_lds_dwordx4 v[234:235], off
	s_waitcnt vmcnt(8)
	s_waitcnt lgkmcnt(0)
	s_barrier
	s_setprio 1
	s_waitcnt lgkmcnt(0)
	v_mfma_f32_16x16x32_bf16 v[64:67], v[168:171], v[148:151], 0
	v_mfma_f32_16x16x32_bf16 v[80:83], v[168:171], v[156:159], 0
	v_mfma_f32_16x16x32_bf16 v[96:99], v[168:171], v[184:187], 0
	v_mfma_f32_16x16x32_bf16 v[112:115], v[168:171], v[192:195], 0
	v_mfma_f32_16x16x32_bf16 v[64:67], v[176:179], v[152:155], v[64:67]
	v_mfma_f32_16x16x32_bf16 v[68:71], v[240:243], v[148:151], 0
	v_mfma_f32_16x16x32_bf16 v[80:83], v[176:179], v[180:183], v[80:83]
	v_mfma_f32_16x16x32_bf16 v[84:87], v[240:243], v[156:159], 0
	v_mfma_f32_16x16x32_bf16 v[96:99], v[176:179], v[188:191], v[96:99]
	v_mfma_f32_16x16x32_bf16 v[112:115], v[176:179], v[196:199], v[112:115]
	v_mfma_f32_16x16x32_bf16 v[116:119], v[240:243], v[192:195], 0
	v_mfma_f32_16x16x32_bf16 v[68:71], v[128:131], v[152:155], v[68:71]
	v_mfma_f32_16x16x32_bf16 v[84:87], v[128:131], v[180:183], v[84:87]
	v_mfma_f32_16x16x32_bf16 v[100:103], v[240:243], v[184:187], 0
	v_mfma_f32_16x16x32_bf16 v[116:119], v[128:131], v[196:199], v[116:119]
	v_mfma_f32_16x16x32_bf16 v[100:103], v[128:131], v[188:191], v[100:103]
	s_setprio 0
	s_setprio 1
	v_mfma_f32_16x16x32_bf16 v[72:75], v[132:135], v[148:151], 0
	v_mfma_f32_16x16x32_bf16 v[76:79], v[140:143], v[148:151], 0
	v_mfma_f32_16x16x32_bf16 v[72:75], v[136:139], v[152:155], v[72:75]
	v_mfma_f32_16x16x32_bf16 v[76:79], v[144:147], v[152:155], v[76:79]
	v_mfma_f32_16x16x32_bf16 v[88:91], v[132:135], v[156:159], 0
	v_mfma_f32_16x16x32_bf16 v[92:95], v[140:143], v[156:159], 0
	v_mfma_f32_16x16x32_bf16 v[104:107], v[132:135], v[184:187], 0
	v_mfma_f32_16x16x32_bf16 v[120:123], v[132:135], v[192:195], 0
	v_mfma_f32_16x16x32_bf16 v[88:91], v[136:139], v[180:183], v[88:91]
	v_mfma_f32_16x16x32_bf16 v[92:95], v[144:147], v[180:183], v[92:95]
	v_mfma_f32_16x16x32_bf16 v[104:107], v[136:139], v[188:191], v[104:107]
	v_mfma_f32_16x16x32_bf16 v[108:111], v[140:143], v[184:187], 0
	v_mfma_f32_16x16x32_bf16 v[120:123], v[136:139], v[196:199], v[120:123]
	v_mfma_f32_16x16x32_bf16 v[124:127], v[140:143], v[192:195], 0
	v_mfma_f32_16x16x32_bf16 v[108:111], v[144:147], v[188:191], v[108:111]
	v_mfma_f32_16x16x32_bf16 v[124:127], v[144:147], v[196:199], v[124:127]
	s_setprio 0
	s_barrier
	s_add_i32 s54, 0, 0x18000
	s_add_i32 s60, 0, 0x1c000
	v_add_u32_e32 v235, s54, v174
	v_add_u32_e32 v234, s60, v174
	ds_read_b128 v[168:171], v235
	ds_read_b128 v[176:179], v235 offset:1024
	ds_read_b128 v[240:243], v235 offset:2048
	ds_read_b128 v[128:131], v235 offset:3072
	ds_read_b128 v[132:135], v234
	ds_read_b128 v[136:139], v234 offset:1024
	ds_read_b128 v[140:143], v234 offset:2048
	ds_read_b128 v[144:147], v234 offset:3072
	s_add_u32 s56, s22, 0x40100
	s_addc_u32 s57, s23, 0
	s_mov_b32 m0, s41
	v_lshl_add_u64 v[166:167], s[56:57], 0, v[160:161]
	ds_read_b128 v[148:151], v175 offset:32768
	ds_read_b128 v[152:155], v175 offset:33792
	ds_read_b128 v[156:159], v175 offset:34816
	ds_read_b128 v[180:183], v175 offset:35840
	ds_read_b128 v[184:187], v175 offset:36864
	ds_read_b128 v[188:191], v175 offset:37888
	ds_read_b128 v[192:195], v175 offset:38912
	ds_read_b128 v[196:199], v175 offset:39936
	global_load_lds_dwordx4 v[166:167], off
	v_lshl_add_u64 v[166:167], s[56:57], 0, v[162:163]
	s_mov_b32 m0, s42
	s_nop 0
	global_load_lds_dwordx4 v[166:167], off
	s_waitcnt vmcnt(8)
	s_waitcnt lgkmcnt(0)
	s_barrier
	s_setprio 1
	s_waitcnt lgkmcnt(0)
	v_mfma_f32_16x16x32_bf16 v[0:3], v[168:171], v[148:151], v[0:3]
	v_mfma_f32_16x16x32_bf16 v[4:7], v[240:243], v[148:151], v[4:7]
	v_mfma_f32_16x16x32_bf16 v[16:19], v[168:171], v[156:159], v[16:19]
	v_mfma_f32_16x16x32_bf16 v[20:23], v[240:243], v[156:159], v[20:23]
	v_mfma_f32_16x16x32_bf16 v[32:35], v[168:171], v[184:187], v[32:35]
	v_mfma_f32_16x16x32_bf16 v[36:39], v[240:243], v[184:187], v[36:39]
	v_mfma_f32_16x16x32_bf16 v[48:51], v[168:171], v[192:195], v[48:51]
	v_mfma_f32_16x16x32_bf16 v[52:55], v[240:243], v[192:195], v[52:55]
	v_mfma_f32_16x16x32_bf16 v[0:3], v[176:179], v[152:155], v[0:3]
	v_mfma_f32_16x16x32_bf16 v[4:7], v[128:131], v[152:155], v[4:7]
	v_mfma_f32_16x16x32_bf16 v[16:19], v[176:179], v[180:183], v[16:19]
	v_mfma_f32_16x16x32_bf16 v[20:23], v[128:131], v[180:183], v[20:23]
	v_mfma_f32_16x16x32_bf16 v[32:35], v[176:179], v[188:191], v[32:35]
	v_mfma_f32_16x16x32_bf16 v[36:39], v[128:131], v[188:191], v[36:39]
	v_mfma_f32_16x16x32_bf16 v[48:51], v[176:179], v[196:199], v[48:51]
	v_mfma_f32_16x16x32_bf16 v[52:55], v[128:131], v[196:199], v[52:55]
	s_setprio 0
	s_setprio 1
	v_mfma_f32_16x16x32_bf16 v[8:11], v[132:135], v[148:151], v[8:11]
	v_mfma_f32_16x16x32_bf16 v[24:27], v[132:135], v[156:159], v[24:27]
	v_mfma_f32_16x16x32_bf16 v[28:31], v[140:143], v[156:159], v[28:31]
	v_mfma_f32_16x16x32_bf16 v[44:47], v[140:143], v[184:187], v[44:47]
	v_mfma_f32_16x16x32_bf16 v[56:59], v[132:135], v[192:195], v[56:59]
	v_mfma_f32_16x16x32_bf16 v[60:63], v[140:143], v[192:195], v[60:63]
	v_mfma_f32_16x16x32_bf16 v[8:11], v[136:139], v[152:155], v[8:11]
	v_mfma_f32_16x16x32_bf16 v[12:15], v[140:143], v[148:151], v[12:15]
	v_mfma_f32_16x16x32_bf16 v[24:27], v[136:139], v[180:183], v[24:27]
	v_mfma_f32_16x16x32_bf16 v[28:31], v[144:147], v[180:183], v[28:31]
	v_mfma_f32_16x16x32_bf16 v[40:43], v[132:135], v[184:187], v[40:43]
	v_mfma_f32_16x16x32_bf16 v[44:47], v[144:147], v[188:191], v[44:47]
	v_mfma_f32_16x16x32_bf16 v[56:59], v[136:139], v[196:199], v[56:59]
	v_mfma_f32_16x16x32_bf16 v[60:63], v[144:147], v[196:199], v[60:63]
	v_mfma_f32_16x16x32_bf16 v[12:15], v[144:147], v[152:155], v[12:15]
	v_mfma_f32_16x16x32_bf16 v[40:43], v[136:139], v[188:191], v[40:43]
	s_setprio 0
	s_barrier
	s_add_i32 s56, s54, s38
	s_mov_b64 s[62:63], 0x180
	s_add_i32 s54, s56, 0x2000
	s_add_u32 s68, s24, s62
	s_addc_u32 s69, s25, s63
	v_lshl_add_u64 v[166:167], s[68:69], 0, v[232:233]
	s_mov_b32 m0, s56
	s_add_u32 s68, s24, s62
	s_addc_u32 s69, s25, s63
	s_add_u32 s58, s24, 0x10180
	ds_read_b128 v[148:151], v175 offset:49152
	ds_read_b128 v[152:155], v175 offset:50176
	ds_read_b128 v[156:159], v175 offset:51200
	ds_read_b128 v[180:183], v175 offset:52224
	ds_read_b128 v[184:187], v175 offset:53248
	ds_read_b128 v[188:191], v175 offset:54272
	ds_read_b128 v[192:195], v175 offset:55296
	ds_read_b128 v[196:199], v175 offset:56320
	global_load_lds_dwordx4 v[166:167], off
	v_lshl_add_u64 v[166:167], s[68:69], 0, v[164:165]
	s_mov_b32 m0, s54
	s_addc_u32 s59, s25, 0
	s_add_i32 s24, s60, s38
	global_load_lds_dwordx4 v[166:167], off
	v_lshl_add_u64 v[166:167], s[58:59], 0, v[232:233]
	s_mov_b32 m0, s24
	s_add_i32 s25, s24, 0x2000
	global_load_lds_dwordx4 v[166:167], off
	v_lshl_add_u64 v[166:167], s[58:59], 0, v[164:165]
	s_mov_b32 m0, s25
	s_nop 0
	global_load_lds_dwordx4 v[166:167], off
	s_add_u32 s68, s22, s62
	s_addc_u32 s69, s23, s63
	v_lshl_add_u64 v[166:167], s[68:69], 0, v[160:161]
	s_mov_b32 m0, s47
	s_nop 0
	global_load_lds_dwordx4 v[166:167], off
	s_add_u32 s68, s22, s62
	s_addc_u32 s69, s23, s63
	v_lshl_add_u64 v[166:167], s[68:69], 0, v[162:163]
	s_mov_b32 m0, s48
	s_nop 0
	global_load_lds_dwordx4 v[166:167], off
	s_waitcnt vmcnt(8)
	s_waitcnt lgkmcnt(0)
	s_barrier
	s_setprio 1
	s_waitcnt lgkmcnt(0)
	v_mfma_f32_16x16x32_bf16 v[64:67], v[168:171], v[148:151], v[64:67]
	v_mfma_f32_16x16x32_bf16 v[68:71], v[240:243], v[148:151], v[68:71]
	v_mfma_f32_16x16x32_bf16 v[84:87], v[240:243], v[156:159], v[84:87]
	v_mfma_f32_16x16x32_bf16 v[96:99], v[168:171], v[184:187], v[96:99]
	v_mfma_f32_16x16x32_bf16 v[112:115], v[168:171], v[192:195], v[112:115]
	v_mfma_f32_16x16x32_bf16 v[116:119], v[240:243], v[192:195], v[116:119]
	v_mfma_f32_16x16x32_bf16 v[64:67], v[176:179], v[152:155], v[64:67]
	v_mfma_f32_16x16x32_bf16 v[68:71], v[128:131], v[152:155], v[68:71]
	v_mfma_f32_16x16x32_bf16 v[80:83], v[168:171], v[156:159], v[80:83]
	v_mfma_f32_16x16x32_bf16 v[84:87], v[128:131], v[180:183], v[84:87]
	v_mfma_f32_16x16x32_bf16 v[96:99], v[176:179], v[188:191], v[96:99]
	v_mfma_f32_16x16x32_bf16 v[100:103], v[240:243], v[184:187], v[100:103]
	v_mfma_f32_16x16x32_bf16 v[112:115], v[176:179], v[196:199], v[112:115]
	v_mfma_f32_16x16x32_bf16 v[116:119], v[128:131], v[196:199], v[116:119]
	v_mfma_f32_16x16x32_bf16 v[80:83], v[176:179], v[180:183], v[80:83]
	v_mfma_f32_16x16x32_bf16 v[100:103], v[128:131], v[188:191], v[100:103]
	s_setprio 0
	s_setprio 1
	v_mfma_f32_16x16x32_bf16 v[72:75], v[132:135], v[148:151], v[72:75]
	v_mfma_f32_16x16x32_bf16 v[76:79], v[140:143], v[148:151], v[76:79]
	v_mfma_f32_16x16x32_bf16 v[88:91], v[132:135], v[156:159], v[88:91]
	v_mfma_f32_16x16x32_bf16 v[92:95], v[140:143], v[156:159], v[92:95]
	v_mfma_f32_16x16x32_bf16 v[104:107], v[132:135], v[184:187], v[104:107]
	v_mfma_f32_16x16x32_bf16 v[108:111], v[140:143], v[184:187], v[108:111]
	v_mfma_f32_16x16x32_bf16 v[124:127], v[140:143], v[192:195], v[124:127]
	v_mfma_f32_16x16x32_bf16 v[72:75], v[136:139], v[152:155], v[72:75]
	v_mfma_f32_16x16x32_bf16 v[76:79], v[144:147], v[152:155], v[76:79]
	v_mfma_f32_16x16x32_bf16 v[92:95], v[144:147], v[180:183], v[92:95]
	v_mfma_f32_16x16x32_bf16 v[104:107], v[136:139], v[188:191], v[104:107]
	v_mfma_f32_16x16x32_bf16 v[108:111], v[144:147], v[188:191], v[108:111]
	v_mfma_f32_16x16x32_bf16 v[120:123], v[132:135], v[192:195], v[120:123]
	v_mfma_f32_16x16x32_bf16 v[124:127], v[144:147], v[196:199], v[124:127]
	v_mfma_f32_16x16x32_bf16 v[88:91], v[136:139], v[180:183], v[88:91]
	v_mfma_f32_16x16x32_bf16 v[120:123], v[136:139], v[196:199], v[120:123]
	s_setprio 0
	s_barrier
	ds_read_b128 v[168:171], v253
	ds_read_b128 v[176:179], v253 offset:1024
	ds_read_b128 v[240:243], v253 offset:2048
	ds_read_b128 v[128:131], v253 offset:3072
	ds_read_b128 v[132:135], v252
	ds_read_b128 v[136:139], v252 offset:1024
	ds_read_b128 v[140:143], v252 offset:2048
	ds_read_b128 v[144:147], v252 offset:3072
	s_add_u32 s22, s22, 0x40180
	s_addc_u32 s23, s23, 0
	s_mov_b32 m0, s55
	v_lshl_add_u64 v[252:253], s[22:23], 0, v[160:161]
	ds_read_b128 v[148:151], v175
	ds_read_b128 v[152:155], v175 offset:1024
	ds_read_b128 v[156:159], v175 offset:2048
	ds_read_b128 v[180:183], v175 offset:3072
	ds_read_b128 v[184:187], v175 offset:4096
	ds_read_b128 v[188:191], v175 offset:5120
	ds_read_b128 v[192:195], v175 offset:6144
	ds_read_b128 v[196:199], v175 offset:7168
	global_load_lds_dwordx4 v[252:253], off
	v_lshl_add_u64 v[252:253], s[22:23], 0, v[162:163]
	s_mov_b32 m0, s13
	s_nop 0
	global_load_lds_dwordx4 v[252:253], off
	s_waitcnt vmcnt(8)
	s_waitcnt lgkmcnt(0)
	s_barrier
	s_setprio 1
	s_waitcnt lgkmcnt(0)
	v_mfma_f32_16x16x32_bf16 v[0:3], v[168:171], v[148:151], v[0:3]
	v_mfma_f32_16x16x32_bf16 v[4:7], v[240:243], v[148:151], v[4:7]
	v_mfma_f32_16x16x32_bf16 v[16:19], v[168:171], v[156:159], v[16:19]
	v_mfma_f32_16x16x32_bf16 v[20:23], v[240:243], v[156:159], v[20:23]
	v_mfma_f32_16x16x32_bf16 v[32:35], v[168:171], v[184:187], v[32:35]
	v_mfma_f32_16x16x32_bf16 v[36:39], v[240:243], v[184:187], v[36:39]
	v_mfma_f32_16x16x32_bf16 v[48:51], v[168:171], v[192:195], v[48:51]
	v_mfma_f32_16x16x32_bf16 v[0:3], v[176:179], v[152:155], v[0:3]
	v_mfma_f32_16x16x32_bf16 v[4:7], v[128:131], v[152:155], v[4:7]
	v_mfma_f32_16x16x32_bf16 v[16:19], v[176:179], v[180:183], v[16:19]
	v_mfma_f32_16x16x32_bf16 v[20:23], v[128:131], v[180:183], v[20:23]
	v_mfma_f32_16x16x32_bf16 v[32:35], v[176:179], v[188:191], v[32:35]
	v_mfma_f32_16x16x32_bf16 v[36:39], v[128:131], v[188:191], v[36:39]
	v_mfma_f32_16x16x32_bf16 v[48:51], v[176:179], v[196:199], v[48:51]
	v_mfma_f32_16x16x32_bf16 v[52:55], v[240:243], v[192:195], v[52:55]
	v_mfma_f32_16x16x32_bf16 v[52:55], v[128:131], v[196:199], v[52:55]
	s_setprio 0
	s_setprio 1
	v_mfma_f32_16x16x32_bf16 v[8:11], v[132:135], v[148:151], v[8:11]
	v_mfma_f32_16x16x32_bf16 v[24:27], v[132:135], v[156:159], v[24:27]
	v_mfma_f32_16x16x32_bf16 v[28:31], v[140:143], v[156:159], v[28:31]
	v_mfma_f32_16x16x32_bf16 v[44:47], v[140:143], v[184:187], v[44:47]
	v_mfma_f32_16x16x32_bf16 v[56:59], v[132:135], v[192:195], v[56:59]
	v_mfma_f32_16x16x32_bf16 v[60:63], v[140:143], v[192:195], v[60:63]
	v_mfma_f32_16x16x32_bf16 v[8:11], v[136:139], v[152:155], v[8:11]
	v_mfma_f32_16x16x32_bf16 v[12:15], v[140:143], v[148:151], v[12:15]
	v_mfma_f32_16x16x32_bf16 v[24:27], v[136:139], v[180:183], v[24:27]
	v_mfma_f32_16x16x32_bf16 v[28:31], v[144:147], v[180:183], v[28:31]
	v_mfma_f32_16x16x32_bf16 v[40:43], v[132:135], v[184:187], v[40:43]
	v_mfma_f32_16x16x32_bf16 v[44:47], v[144:147], v[188:191], v[44:47]
	v_mfma_f32_16x16x32_bf16 v[56:59], v[136:139], v[196:199], v[56:59]
	v_mfma_f32_16x16x32_bf16 v[60:63], v[144:147], v[196:199], v[60:63]
	v_mfma_f32_16x16x32_bf16 v[12:15], v[144:147], v[152:155], v[12:15]
	v_mfma_f32_16x16x32_bf16 v[40:43], v[136:139], v[188:191], v[40:43]
	s_setprio 0
	s_barrier
	s_mov_b32 m0, s53
	v_lshl_add_u64 v[252:253], s[26:27], 0, v[232:233]
	s_add_u32 s22, s26, 0x10000
	ds_read_b128 v[148:151], v175 offset:16384
	ds_read_b128 v[152:155], v175 offset:17408
	ds_read_b128 v[156:159], v175 offset:18432
	ds_read_b128 v[180:183], v175 offset:19456
	ds_read_b128 v[184:187], v175 offset:20480
	ds_read_b128 v[188:191], v175 offset:21504
	ds_read_b128 v[192:195], v175 offset:22528
	ds_read_b128 v[196:199], v175 offset:23552
	global_load_lds_dwordx4 v[252:253], off
	v_lshl_add_u64 v[252:253], s[26:27], 0, v[164:165]
	s_mov_b32 m0, s15
	s_addc_u32 s23, s27, 0
	global_load_lds_dwordx4 v[252:253], off
	v_lshl_add_u64 v[252:253], s[22:23], 0, v[232:233]
	s_mov_b32 m0, s21
	v_lshl_add_u64 v[166:167], s[28:29], 0, v[160:161]
	global_load_lds_dwordx4 v[252:253], off
	v_lshl_add_u64 v[252:253], s[22:23], 0, v[164:165]
	s_mov_b32 m0, s52
	v_lshl_add_u64 v[172:173], s[28:29], 0, v[162:163]
	global_load_lds_dwordx4 v[252:253], off
	s_mov_b32 m0, s39
	s_nop 0
	global_load_lds_dwordx4 v[166:167], off
	s_mov_b32 m0, s40
	s_nop 0
	global_load_lds_dwordx4 v[172:173], off
	s_waitcnt vmcnt(8)
	s_waitcnt lgkmcnt(0)
	s_barrier
	s_setprio 1
	s_waitcnt lgkmcnt(0)
	v_mfma_f32_16x16x32_bf16 v[64:67], v[168:171], v[148:151], v[64:67]
	v_mfma_f32_16x16x32_bf16 v[64:67], v[176:179], v[152:155], v[64:67]
	v_mfma_f32_16x16x32_bf16 v[68:71], v[240:243], v[148:151], v[68:71]
	v_mfma_f32_16x16x32_bf16 v[68:71], v[128:131], v[152:155], v[68:71]
	v_mfma_f32_16x16x32_bf16 v[80:83], v[168:171], v[156:159], v[80:83]
	v_mfma_f32_16x16x32_bf16 v[80:83], v[176:179], v[180:183], v[80:83]
	v_mfma_f32_16x16x32_bf16 v[84:87], v[240:243], v[156:159], v[84:87]
	v_mfma_f32_16x16x32_bf16 v[84:87], v[128:131], v[180:183], v[84:87]
	v_mfma_f32_16x16x32_bf16 v[96:99], v[168:171], v[184:187], v[96:99]
	v_mfma_f32_16x16x32_bf16 v[112:115], v[168:171], v[192:195], v[112:115]
	v_mfma_f32_16x16x32_bf16 v[116:119], v[240:243], v[192:195], v[116:119]
	v_mfma_f32_16x16x32_bf16 v[96:99], v[176:179], v[188:191], v[96:99]
	v_mfma_f32_16x16x32_bf16 v[100:103], v[240:243], v[184:187], v[100:103]
	v_mfma_f32_16x16x32_bf16 v[112:115], v[176:179], v[196:199], v[112:115]
	v_mfma_f32_16x16x32_bf16 v[116:119], v[128:131], v[196:199], v[116:119]
	v_mfma_f32_16x16x32_bf16 v[100:103], v[128:131], v[188:191], v[100:103]
	s_setprio 0
	s_setprio 1
	v_mfma_f32_16x16x32_bf16 v[72:75], v[132:135], v[148:151], v[72:75]
	v_mfma_f32_16x16x32_bf16 v[72:75], v[136:139], v[152:155], v[72:75]
	v_mfma_f32_16x16x32_bf16 v[76:79], v[140:143], v[148:151], v[76:79]
	v_mfma_f32_16x16x32_bf16 v[76:79], v[144:147], v[152:155], v[76:79]
	v_mfma_f32_16x16x32_bf16 v[88:91], v[132:135], v[156:159], v[88:91]
	v_mfma_f32_16x16x32_bf16 v[88:91], v[136:139], v[180:183], v[88:91]
	v_mfma_f32_16x16x32_bf16 v[92:95], v[140:143], v[156:159], v[92:95]
	v_mfma_f32_16x16x32_bf16 v[92:95], v[144:147], v[180:183], v[92:95]
	v_mfma_f32_16x16x32_bf16 v[104:107], v[132:135], v[184:187], v[104:107]
	v_mfma_f32_16x16x32_bf16 v[104:107], v[136:139], v[188:191], v[104:107]
	v_mfma_f32_16x16x32_bf16 v[108:111], v[140:143], v[184:187], v[108:111]
	v_mfma_f32_16x16x32_bf16 v[108:111], v[144:147], v[188:191], v[108:111]
	v_mfma_f32_16x16x32_bf16 v[120:123], v[132:135], v[192:195], v[120:123]
	v_mfma_f32_16x16x32_bf16 v[120:123], v[136:139], v[196:199], v[120:123]
	v_mfma_f32_16x16x32_bf16 v[124:127], v[140:143], v[192:195], v[124:127]
	v_mfma_f32_16x16x32_bf16 v[124:127], v[144:147], v[196:199], v[124:127]
	s_setprio 0
	s_barrier
	s_nop 4
	ds_read_b128 v[168:171], v235
	ds_read_b128 v[176:179], v235 offset:1024
	ds_read_b128 v[240:243], v235 offset:2048
	ds_read_b128 v[128:131], v235 offset:3072
	ds_read_b128 v[132:135], v234
	ds_read_b128 v[136:139], v234 offset:1024
	ds_read_b128 v[140:143], v234 offset:2048
	ds_read_b128 v[144:147], v234 offset:3072
	s_add_u32 s22, s28, 0x40000
	s_addc_u32 s23, s29, 0
	s_mov_b32 m0, s41
	v_lshl_add_u64 v[252:253], s[22:23], 0, v[160:161]
	ds_read_b128 v[148:151], v175 offset:32768
	ds_read_b128 v[152:155], v175 offset:33792
	ds_read_b128 v[156:159], v175 offset:34816
	ds_read_b128 v[180:183], v175 offset:35840
	ds_read_b128 v[184:187], v175 offset:36864
	ds_read_b128 v[188:191], v175 offset:37888
	ds_read_b128 v[192:195], v175 offset:38912
	ds_read_b128 v[196:199], v175 offset:39936
	global_load_lds_dwordx4 v[252:253], off
	v_lshl_add_u64 v[252:253], s[22:23], 0, v[162:163]
	s_mov_b32 m0, s42
	s_nop 0
	global_load_lds_dwordx4 v[252:253], off
	s_waitcnt vmcnt(8)
	s_waitcnt lgkmcnt(0)
	s_barrier
	s_setprio 1
	s_waitcnt lgkmcnt(0)
	v_mfma_f32_16x16x32_bf16 v[0:3], v[168:171], v[148:151], v[0:3]
	v_mfma_f32_16x16x32_bf16 v[0:3], v[176:179], v[152:155], v[0:3]
	v_mfma_f32_16x16x32_bf16 v[4:7], v[240:243], v[148:151], v[4:7]
	v_mfma_f32_16x16x32_bf16 v[4:7], v[128:131], v[152:155], v[4:7]
	v_mfma_f32_16x16x32_bf16 v[16:19], v[168:171], v[156:159], v[16:19]
	v_mfma_f32_16x16x32_bf16 v[16:19], v[176:179], v[180:183], v[16:19]
	v_mfma_f32_16x16x32_bf16 v[20:23], v[240:243], v[156:159], v[20:23]
	v_mfma_f32_16x16x32_bf16 v[20:23], v[128:131], v[180:183], v[20:23]
	v_mfma_f32_16x16x32_bf16 v[32:35], v[168:171], v[184:187], v[32:35]
	v_mfma_f32_16x16x32_bf16 v[32:35], v[176:179], v[188:191], v[32:35]
	v_mfma_f32_16x16x32_bf16 v[36:39], v[240:243], v[184:187], v[36:39]
	v_mfma_f32_16x16x32_bf16 v[36:39], v[128:131], v[188:191], v[36:39]
	v_mfma_f32_16x16x32_bf16 v[48:51], v[168:171], v[192:195], v[48:51]
	v_mfma_f32_16x16x32_bf16 v[48:51], v[176:179], v[196:199], v[48:51]
	v_mfma_f32_16x16x32_bf16 v[52:55], v[240:243], v[192:195], v[52:55]
	v_mfma_f32_16x16x32_bf16 v[52:55], v[128:131], v[196:199], v[52:55]
	s_setprio 0
	s_setprio 1
	v_mfma_f32_16x16x32_bf16 v[12:15], v[140:143], v[148:151], v[12:15]
	v_mfma_f32_16x16x32_bf16 v[12:15], v[144:147], v[152:155], v[12:15]
	v_mfma_f32_16x16x32_bf16 v[24:27], v[132:135], v[156:159], v[24:27]
	v_mfma_f32_16x16x32_bf16 v[24:27], v[136:139], v[180:183], v[24:27]
	v_mfma_f32_16x16x32_bf16 v[28:31], v[140:143], v[156:159], v[28:31]
	v_mfma_f32_16x16x32_bf16 v[8:11], v[132:135], v[148:151], v[8:11]
	v_mfma_f32_16x16x32_bf16 v[28:31], v[144:147], v[180:183], v[28:31]
	v_mfma_f32_16x16x32_bf16 v[40:43], v[132:135], v[184:187], v[40:43]
	v_mfma_f32_16x16x32_bf16 v[8:11], v[136:139], v[152:155], v[8:11]
	v_mfma_f32_16x16x32_bf16 v[40:43], v[136:139], v[188:191], v[40:43]
	v_mfma_f32_16x16x32_bf16 v[44:47], v[140:143], v[184:187], v[44:47]
	v_mfma_f32_16x16x32_bf16 v[44:47], v[144:147], v[188:191], v[44:47]
	v_mfma_f32_16x16x32_bf16 v[56:59], v[132:135], v[192:195], v[56:59]
	v_mfma_f32_16x16x32_bf16 v[56:59], v[136:139], v[196:199], v[56:59]
	v_mfma_f32_16x16x32_bf16 v[60:63], v[140:143], v[192:195], v[60:63]
	v_mfma_f32_16x16x32_bf16 v[60:63], v[144:147], v[196:199], v[60:63]
	s_setprio 0
	s_barrier
	s_mov_b32 m0, s56
	s_add_u32 s68, s26, s94
	s_addc_u32 s69, s27, s95
	v_lshl_add_u64 v[252:253], s[68:69], 0, v[232:233]
	s_add_u32 s68, s26, s94
	s_addc_u32 s69, s27, s95
	s_add_u32 s22, s26, 0x10080
	s_nop 1
	ds_read_b128 v[148:151], v175 offset:49152
	ds_read_b128 v[152:155], v175 offset:50176
	ds_read_b128 v[156:159], v175 offset:51200
	ds_read_b128 v[180:183], v175 offset:52224
	ds_read_b128 v[184:187], v175 offset:53248
	ds_read_b128 v[188:191], v175 offset:54272
	ds_read_b128 v[192:195], v175 offset:55296
	ds_read_b128 v[196:199], v175 offset:56320
	global_load_lds_dwordx4 v[252:253], off
	v_lshl_add_u64 v[252:253], s[68:69], 0, v[164:165]
	s_mov_b32 m0, s54
	s_addc_u32 s23, s27, 0
	global_load_lds_dwordx4 v[252:253], off
	v_lshl_add_u64 v[252:253], s[22:23], 0, v[232:233]
	s_mov_b32 m0, s24
	s_nop 0
	global_load_lds_dwordx4 v[252:253], off
	v_lshl_add_u64 v[252:253], s[22:23], 0, v[164:165]
	s_mov_b32 m0, s25
	s_nop 0
	global_load_lds_dwordx4 v[252:253], off
	s_add_u32 s68, s28, s94
	s_addc_u32 s69, s29, s95
	v_lshl_add_u64 v[252:253], s[68:69], 0, v[160:161]
	s_mov_b32 m0, s47
	s_nop 0
	global_load_lds_dwordx4 v[252:253], off
	s_add_u32 s68, s28, s94
	s_addc_u32 s69, s29, s95
	v_lshl_add_u64 v[252:253], s[68:69], 0, v[162:163]
	s_mov_b32 m0, s48
	s_nop 0
	global_load_lds_dwordx4 v[252:253], off
	s_waitcnt vmcnt(8)
	s_waitcnt lgkmcnt(0)
	s_barrier
	s_setprio 1
	s_waitcnt lgkmcnt(0)
	v_mfma_f32_16x16x32_bf16 v[64:67], v[168:171], v[148:151], v[64:67]
	v_mfma_f32_16x16x32_bf16 v[64:67], v[176:179], v[152:155], v[64:67]
	v_mfma_f32_16x16x32_bf16 v[68:71], v[240:243], v[148:151], v[68:71]
	v_mfma_f32_16x16x32_bf16 v[68:71], v[128:131], v[152:155], v[68:71]
	v_mfma_f32_16x16x32_bf16 v[80:83], v[168:171], v[156:159], v[80:83]
	v_mfma_f32_16x16x32_bf16 v[80:83], v[176:179], v[180:183], v[80:83]
	v_mfma_f32_16x16x32_bf16 v[84:87], v[240:243], v[156:159], v[84:87]
	v_mfma_f32_16x16x32_bf16 v[84:87], v[128:131], v[180:183], v[84:87]
	v_mfma_f32_16x16x32_bf16 v[96:99], v[168:171], v[184:187], v[96:99]
	v_mfma_f32_16x16x32_bf16 v[112:115], v[168:171], v[192:195], v[112:115]
	v_mfma_f32_16x16x32_bf16 v[96:99], v[176:179], v[188:191], v[96:99]
	v_mfma_f32_16x16x32_bf16 v[100:103], v[240:243], v[184:187], v[100:103]
	v_mfma_f32_16x16x32_bf16 v[112:115], v[176:179], v[196:199], v[112:115]
	v_mfma_f32_16x16x32_bf16 v[116:119], v[240:243], v[192:195], v[116:119]
	v_mfma_f32_16x16x32_bf16 v[100:103], v[128:131], v[188:191], v[100:103]
	v_mfma_f32_16x16x32_bf16 v[116:119], v[128:131], v[196:199], v[116:119]
	s_setprio 0
	s_setprio 1
	v_mfma_f32_16x16x32_bf16 v[72:75], v[132:135], v[148:151], v[72:75]
	v_mfma_f32_16x16x32_bf16 v[72:75], v[136:139], v[152:155], v[72:75]
	v_mfma_f32_16x16x32_bf16 v[76:79], v[140:143], v[148:151], v[76:79]
	v_mfma_f32_16x16x32_bf16 v[76:79], v[144:147], v[152:155], v[76:79]
	v_mfma_f32_16x16x32_bf16 v[88:91], v[132:135], v[156:159], v[88:91]
	v_mfma_f32_16x16x32_bf16 v[88:91], v[136:139], v[180:183], v[88:91]
	v_mfma_f32_16x16x32_bf16 v[92:95], v[140:143], v[156:159], v[92:95]
	v_mfma_f32_16x16x32_bf16 v[92:95], v[144:147], v[180:183], v[92:95]
	v_mfma_f32_16x16x32_bf16 v[104:107], v[132:135], v[184:187], v[104:107]
	v_mfma_f32_16x16x32_bf16 v[104:107], v[136:139], v[188:191], v[104:107]
	v_mfma_f32_16x16x32_bf16 v[108:111], v[140:143], v[184:187], v[108:111]
	v_mfma_f32_16x16x32_bf16 v[108:111], v[144:147], v[188:191], v[108:111]
	v_mfma_f32_16x16x32_bf16 v[120:123], v[132:135], v[192:195], v[120:123]
	v_mfma_f32_16x16x32_bf16 v[120:123], v[136:139], v[196:199], v[120:123]
	v_mfma_f32_16x16x32_bf16 v[124:127], v[140:143], v[192:195], v[124:127]
	v_mfma_f32_16x16x32_bf16 v[124:127], v[144:147], v[196:199], v[124:127]
	s_setprio 0
	s_barrier
	s_andn2_b64 vcc, exec, s[10:11]
	s_cbranch_vccnz .LBB0_1020
	s_barrier
.LBB0_1020:
	s_lshl_b32 s13, s20, 8
	s_lshl_b32 s20, s5, 10
	v_mbcnt_lo_u32_b32 v128, -1, 0
	v_mbcnt_hi_u32_b32 v128, -1, v128
	s_lshl_b32 s4, s4, 8
	v_and_or_b32 v176, v128, 15, s45
	s_ashr_i32 s21, s20, 31
	v_ashrrev_i32_e32 v128, 1, v128
	v_add_u32_e32 v168, s13, v176
	s_or_b32 s4, s4, s46
	s_lshl_b64 s[20:21], s[20:21], 1
	v_and_b32_e32 v128, -8, v128
	s_add_u32 s20, s43, s20
	v_ashrrev_i32_e32 v169, 31, v168
	v_add_u32_e32 v166, s4, v128
	s_addc_u32 s21, s44, s21
	v_lshlrev_b64 v[128:129], 13, v[168:169]
	v_lshl_add_u64 v[128:129], s[20:21], 0, v[128:129]
	v_ashrrev_i32_e32 v167, 31, v166
	v_lshl_add_u64 v[128:129], v[166:167], 1, v[128:129]
	v_lshlrev_b64 v[130:131], 11, v[168:169]
	v_lshl_add_u64 v[130:131], s[8:9], 0, v[130:131]
	v_lshl_add_u64 v[172:173], v[166:167], 1, v[130:131]
	v_mov_b64_e32 v[170:171], v[128:129]
	s_mov_b32 s59, 0
	s_waitcnt lgkmcnt(0)
	v_mbcnt_lo_u32_b32 v177, -1, 0
	v_mbcnt_hi_u32_b32 v177, -1, v177
	s_lshl_b32 s58, s45, 6
	s_lshl_b32 s59, s46, 5
	s_add_i32 s58, s58, s59
	s_add_i32 s58, s58, 0x21000
	s_mov_b32 s59, 0
	v_lshl_add_u32 v177, v177, 4, s58
	s_cmp_eq_u32 s5, 0
	s_cbranch_scc1 .Lmepi_z0
	s_cmp_eq_u32 s5, 3
	s_cbranch_scc1 .Lmepi_z3
	global_load_dwordx4 v[128:131], v[170:171], off nt
	global_load_dwordx4 v[132:135], v[170:171], off offset:256 nt
	s_mov_b32 s58, 0x20000
	v_lshl_add_u64 v[234:235], v[170:171], 0, s[58:59]
	global_load_dwordx4 v[136:139], v[234:235], off nt
	global_load_dwordx4 v[140:143], v[234:235], off offset:256 nt
	s_mov_b32 s58, 0x40000
	v_lshl_add_u64 v[252:253], v[170:171], 0, s[58:59]
	global_load_dwordx4 v[144:147], v[252:253], off nt
	global_load_dwordx4 v[148:151], v[252:253], off offset:256 nt
	s_mov_b32 s58, 0x60000
	v_lshl_add_u64 v[178:179], v[170:171], 0, s[58:59]
	global_load_dwordx4 v[152:155], v[178:179], off nt
	global_load_dwordx4 v[156:159], v[178:179], off offset:256 nt
	s_mov_b32 s58, 0x100000
	v_lshl_add_u64 v[240:241], v[170:171], 0, s[58:59]
	global_load_dwordx4 v[180:183], v[240:241], off nt
	global_load_dwordx4 v[184:187], v[240:241], off offset:256 nt
	s_mov_b32 s58, 0x120000
	v_lshl_add_u64 v[242:243], v[170:171], 0, s[58:59]
	global_load_dwordx4 v[188:191], v[242:243], off nt
	global_load_dwordx4 v[192:195], v[242:243], off offset:256 nt
	ds_read_b128 v[196:199], v177 offset:0
	s_waitcnt vmcnt(11)
	v_lshlrev_b32_e32 v234, 16, v128
	v_and_b32_e32 v235, 0xffff0000, v128
	v_pk_mul_f32 v[0:1], v[0:1], v[234:235]
	v_lshlrev_b32_e32 v252, 16, v129
	v_and_b32_e32 v253, 0xffff0000, v129
	v_pk_mul_f32 v[2:3], v[2:3], v[252:253]
	v_lshlrev_b32_e32 v178, 16, v130
	v_and_b32_e32 v179, 0xffff0000, v130
	v_pk_mul_f32 v[4:5], v[4:5], v[178:179]
	v_lshlrev_b32_e32 v240, 16, v131
	v_and_b32_e32 v241, 0xffff0000, v131
	v_pk_mul_f32 v[6:7], v[6:7], v[240:241]
	v_lshlrev_b32_e32 v242, 16, v200
	v_and_b32_e32 v243, 0xffff0000, v200
	v_pk_add_f32 v[0:1], v[0:1], v[242:243]
	v_lshlrev_b32_e32 v234, 16, v201
	v_and_b32_e32 v235, 0xffff0000, v201
	v_pk_add_f32 v[2:3], v[2:3], v[234:235]
	v_lshlrev_b32_e32 v252, 16, v202
	v_and_b32_e32 v253, 0xffff0000, v202
	v_pk_add_f32 v[4:5], v[4:5], v[252:253]
	v_lshlrev_b32_e32 v178, 16, v203
	v_and_b32_e32 v179, 0xffff0000, v203
	v_pk_add_f32 v[6:7], v[6:7], v[178:179]
	v_cvt_pk_bf16_f32 v200, v0, v1
	v_cvt_pk_bf16_f32 v201, v2, v3
	v_cvt_pk_bf16_f32 v202, v4, v5
	v_cvt_pk_bf16_f32 v203, v6, v7
	s_waitcnt vmcnt(10)
	v_lshlrev_b32_e32 v240, 16, v132
	v_and_b32_e32 v241, 0xffff0000, v132
	v_pk_mul_f32 v[8:9], v[8:9], v[240:241]
	v_lshlrev_b32_e32 v242, 16, v133
	v_and_b32_e32 v243, 0xffff0000, v133
	v_pk_mul_f32 v[10:11], v[10:11], v[242:243]
	v_lshlrev_b32_e32 v234, 16, v134
	v_and_b32_e32 v235, 0xffff0000, v134
	v_pk_mul_f32 v[12:13], v[12:13], v[234:235]
	v_lshlrev_b32_e32 v252, 16, v135
	v_and_b32_e32 v253, 0xffff0000, v135
	v_pk_mul_f32 v[14:15], v[14:15], v[252:253]
	v_lshlrev_b32_e32 v178, 16, v204
	v_and_b32_e32 v179, 0xffff0000, v204
	v_pk_add_f32 v[8:9], v[8:9], v[178:179]
	v_lshlrev_b32_e32 v240, 16, v205
	v_and_b32_e32 v241, 0xffff0000, v205
	v_pk_add_f32 v[10:11], v[10:11], v[240:241]
	v_lshlrev_b32_e32 v242, 16, v206
	v_and_b32_e32 v243, 0xffff0000, v206
	v_pk_add_f32 v[12:13], v[12:13], v[242:243]
	v_lshlrev_b32_e32 v234, 16, v207
	v_and_b32_e32 v235, 0xffff0000, v207
	v_pk_add_f32 v[14:15], v[14:15], v[234:235]
	v_cvt_pk_bf16_f32 v204, v8, v9
	v_cvt_pk_bf16_f32 v205, v10, v11
	v_cvt_pk_bf16_f32 v206, v12, v13
	v_cvt_pk_bf16_f32 v207, v14, v15
	s_mov_b32 s58, 0x140000
	v_lshl_add_u64 v[252:253], v[170:171], 0, s[58:59]
	global_load_dwordx4 v[0:3], v[252:253], off nt
	global_load_dwordx4 v[4:7], v[252:253], off offset:256 nt
	ds_read_b128 v[128:131], v177 offset:8192
	ds_read_b128 v[8:11], v177 offset:16384
	s_waitcnt vmcnt(11)
	v_lshlrev_b32_e32 v178, 16, v136
	v_and_b32_e32 v179, 0xffff0000, v136
	v_pk_mul_f32 v[16:17], v[16:17], v[178:179]
	v_lshlrev_b32_e32 v240, 16, v137
	v_and_b32_e32 v241, 0xffff0000, v137
	v_pk_mul_f32 v[18:19], v[18:19], v[240:241]
	v_lshlrev_b32_e32 v242, 16, v138
	v_and_b32_e32 v243, 0xffff0000, v138
	v_pk_mul_f32 v[20:21], v[20:21], v[242:243]
	v_lshlrev_b32_e32 v234, 16, v139
	v_and_b32_e32 v235, 0xffff0000, v139
	v_pk_mul_f32 v[22:23], v[22:23], v[234:235]
	v_lshlrev_b32_e32 v252, 16, v208
	v_and_b32_e32 v253, 0xffff0000, v208
	v_pk_add_f32 v[16:17], v[16:17], v[252:253]
	v_lshlrev_b32_e32 v178, 16, v209
	v_and_b32_e32 v179, 0xffff0000, v209
	v_pk_add_f32 v[18:19], v[18:19], v[178:179]
	v_lshlrev_b32_e32 v240, 16, v210
	v_and_b32_e32 v241, 0xffff0000, v210
	v_pk_add_f32 v[20:21], v[20:21], v[240:241]
	v_lshlrev_b32_e32 v242, 16, v211
	v_and_b32_e32 v243, 0xffff0000, v211
	v_pk_add_f32 v[22:23], v[22:23], v[242:243]
	v_cvt_pk_bf16_f32 v208, v16, v17
	v_cvt_pk_bf16_f32 v209, v18, v19
	v_cvt_pk_bf16_f32 v210, v20, v21
	v_cvt_pk_bf16_f32 v211, v22, v23
	s_waitcnt vmcnt(10)
	v_lshlrev_b32_e32 v234, 16, v140
	v_and_b32_e32 v235, 0xffff0000, v140
	v_pk_mul_f32 v[24:25], v[24:25], v[234:235]
	v_lshlrev_b32_e32 v252, 16, v141
	v_and_b32_e32 v253, 0xffff0000, v141
	v_pk_mul_f32 v[26:27], v[26:27], v[252:253]
	v_lshlrev_b32_e32 v178, 16, v142
	v_and_b32_e32 v179, 0xffff0000, v142
	v_pk_mul_f32 v[28:29], v[28:29], v[178:179]
	v_lshlrev_b32_e32 v240, 16, v143
	v_and_b32_e32 v241, 0xffff0000, v143
	v_pk_mul_f32 v[30:31], v[30:31], v[240:241]
	v_lshlrev_b32_e32 v242, 16, v212
	v_and_b32_e32 v243, 0xffff0000, v212
	v_pk_add_f32 v[24:25], v[24:25], v[242:243]
	v_lshlrev_b32_e32 v234, 16, v213
	v_and_b32_e32 v235, 0xffff0000, v213
	v_pk_add_f32 v[26:27], v[26:27], v[234:235]
	v_lshlrev_b32_e32 v252, 16, v214
	v_and_b32_e32 v253, 0xffff0000, v214
	v_pk_add_f32 v[28:29], v[28:29], v[252:253]
	v_lshlrev_b32_e32 v178, 16, v215
	v_and_b32_e32 v179, 0xffff0000, v215
	v_pk_add_f32 v[30:31], v[30:31], v[178:179]
	v_cvt_pk_bf16_f32 v212, v24, v25
	v_cvt_pk_bf16_f32 v213, v26, v27
	v_cvt_pk_bf16_f32 v214, v28, v29
	v_cvt_pk_bf16_f32 v215, v30, v31
	s_mov_b32 s58, 0x160000
	v_lshl_add_u64 v[240:241], v[170:171], 0, s[58:59]
	global_load_dwordx4 v[12:15], v[240:241], off nt
	global_load_dwordx4 v[132:135], v[240:241], off offset:256 nt
	s_mov_b32 s58, 0x58000
	v_lshl_add_u64 v[242:243], v[172:173], 0, s[58:59]
	global_load_dwordx4 v[16:19], v[242:243], off
	global_load_dwordx4 v[20:23], v[242:243], off offset:256
	s_waitcnt vmcnt(13)
	v_lshlrev_b32_e32 v234, 16, v144
	v_and_b32_e32 v235, 0xffff0000, v144
	v_pk_mul_f32 v[32:33], v[32:33], v[234:235]
	v_lshlrev_b32_e32 v252, 16, v145
	v_and_b32_e32 v253, 0xffff0000, v145
	v_pk_mul_f32 v[34:35], v[34:35], v[252:253]
	v_lshlrev_b32_e32 v178, 16, v146
	v_and_b32_e32 v179, 0xffff0000, v146
	v_pk_mul_f32 v[36:37], v[36:37], v[178:179]
	v_lshlrev_b32_e32 v240, 16, v147
	v_and_b32_e32 v241, 0xffff0000, v147
	v_pk_mul_f32 v[38:39], v[38:39], v[240:241]
	v_lshlrev_b32_e32 v242, 16, v216
	v_and_b32_e32 v243, 0xffff0000, v216
	v_pk_add_f32 v[32:33], v[32:33], v[242:243]
	v_lshlrev_b32_e32 v234, 16, v217
	v_and_b32_e32 v235, 0xffff0000, v217
	v_pk_add_f32 v[34:35], v[34:35], v[234:235]
	v_lshlrev_b32_e32 v252, 16, v218
	v_and_b32_e32 v253, 0xffff0000, v218
	v_pk_add_f32 v[36:37], v[36:37], v[252:253]
	v_lshlrev_b32_e32 v178, 16, v219
	v_and_b32_e32 v179, 0xffff0000, v219
	v_pk_add_f32 v[38:39], v[38:39], v[178:179]
	v_cvt_pk_bf16_f32 v216, v32, v33
	v_cvt_pk_bf16_f32 v217, v34, v35
	v_cvt_pk_bf16_f32 v218, v36, v37
	v_cvt_pk_bf16_f32 v219, v38, v39
	s_waitcnt vmcnt(12)
	v_lshlrev_b32_e32 v240, 16, v148
	v_and_b32_e32 v241, 0xffff0000, v148
	v_pk_mul_f32 v[40:41], v[40:41], v[240:241]
	v_lshlrev_b32_e32 v242, 16, v149
	v_and_b32_e32 v243, 0xffff0000, v149
	v_pk_mul_f32 v[42:43], v[42:43], v[242:243]
	v_lshlrev_b32_e32 v234, 16, v150
	v_and_b32_e32 v235, 0xffff0000, v150
	v_pk_mul_f32 v[44:45], v[44:45], v[234:235]
	v_lshlrev_b32_e32 v252, 16, v151
	v_and_b32_e32 v253, 0xffff0000, v151
	v_pk_mul_f32 v[46:47], v[46:47], v[252:253]
	v_lshlrev_b32_e32 v178, 16, v220
	v_and_b32_e32 v179, 0xffff0000, v220
	v_pk_add_f32 v[40:41], v[40:41], v[178:179]
	v_lshlrev_b32_e32 v240, 16, v221
	v_and_b32_e32 v241, 0xffff0000, v221
	v_pk_add_f32 v[42:43], v[42:43], v[240:241]
	v_lshlrev_b32_e32 v242, 16, v222
	v_and_b32_e32 v243, 0xffff0000, v222
	v_pk_add_f32 v[44:45], v[44:45], v[242:243]
	v_lshlrev_b32_e32 v234, 16, v223
	v_and_b32_e32 v235, 0xffff0000, v223
	v_pk_add_f32 v[46:47], v[46:47], v[234:235]
	v_cvt_pk_bf16_f32 v220, v40, v41
	v_cvt_pk_bf16_f32 v221, v42, v43
	v_cvt_pk_bf16_f32 v222, v44, v45
	v_cvt_pk_bf16_f32 v223, v46, v47
	s_waitcnt vmcnt(11)
	v_lshlrev_b32_e32 v252, 16, v152
	v_and_b32_e32 v253, 0xffff0000, v152
	v_pk_mul_f32 v[48:49], v[48:49], v[252:253]
	v_lshlrev_b32_e32 v178, 16, v153
	v_and_b32_e32 v179, 0xffff0000, v153
	v_pk_mul_f32 v[50:51], v[50:51], v[178:179]
	v_lshlrev_b32_e32 v240, 16, v154
	v_and_b32_e32 v241, 0xffff0000, v154
	v_pk_mul_f32 v[52:53], v[52:53], v[240:241]
	v_lshlrev_b32_e32 v242, 16, v155
	v_and_b32_e32 v243, 0xffff0000, v155
	v_pk_mul_f32 v[54:55], v[54:55], v[242:243]
	v_lshlrev_b32_e32 v234, 16, v224
	v_and_b32_e32 v235, 0xffff0000, v224
	v_pk_add_f32 v[48:49], v[48:49], v[234:235]
	v_lshlrev_b32_e32 v252, 16, v225
	v_and_b32_e32 v253, 0xffff0000, v225
	v_pk_add_f32 v[50:51], v[50:51], v[252:253]
	v_lshlrev_b32_e32 v178, 16, v226
	v_and_b32_e32 v179, 0xffff0000, v226
	v_pk_add_f32 v[52:53], v[52:53], v[178:179]
	v_lshlrev_b32_e32 v240, 16, v227
	v_and_b32_e32 v241, 0xffff0000, v227
	v_pk_add_f32 v[54:55], v[54:55], v[240:241]
	v_cvt_pk_bf16_f32 v224, v48, v49
	v_cvt_pk_bf16_f32 v225, v50, v51
	v_cvt_pk_bf16_f32 v226, v52, v53
	v_cvt_pk_bf16_f32 v227, v54, v55
	s_waitcnt vmcnt(10)
	v_lshlrev_b32_e32 v242, 16, v156
	v_and_b32_e32 v243, 0xffff0000, v156
	v_pk_mul_f32 v[56:57], v[56:57], v[242:243]
	v_lshlrev_b32_e32 v234, 16, v157
	v_and_b32_e32 v235, 0xffff0000, v157
	v_pk_mul_f32 v[58:59], v[58:59], v[234:235]
	v_lshlrev_b32_e32 v252, 16, v158
	v_and_b32_e32 v253, 0xffff0000, v158
	v_pk_mul_f32 v[60:61], v[60:61], v[252:253]
	v_lshlrev_b32_e32 v178, 16, v159
	v_and_b32_e32 v179, 0xffff0000, v159
	v_pk_mul_f32 v[62:63], v[62:63], v[178:179]
	v_lshlrev_b32_e32 v240, 16, v228
	v_and_b32_e32 v241, 0xffff0000, v228
	v_pk_add_f32 v[56:57], v[56:57], v[240:241]
	v_lshlrev_b32_e32 v242, 16, v229
	v_and_b32_e32 v243, 0xffff0000, v229
	v_pk_add_f32 v[58:59], v[58:59], v[242:243]
	v_lshlrev_b32_e32 v234, 16, v230
	v_and_b32_e32 v235, 0xffff0000, v230
	v_pk_add_f32 v[60:61], v[60:61], v[234:235]
	v_lshlrev_b32_e32 v252, 16, v231
	v_and_b32_e32 v253, 0xffff0000, v231
	v_pk_add_f32 v[62:63], v[62:63], v[252:253]
	v_cvt_pk_bf16_f32 v228, v56, v57
	v_cvt_pk_bf16_f32 v229, v58, v59
	v_cvt_pk_bf16_f32 v230, v60, v61
	v_cvt_pk_bf16_f32 v231, v62, v63
	s_waitcnt vmcnt(9)
	v_lshlrev_b32_e32 v178, 16, v180
	v_and_b32_e32 v179, 0xffff0000, v180
	v_pk_mul_f32 v[64:65], v[64:65], v[178:179]
	v_lshlrev_b32_e32 v240, 16, v181
	v_and_b32_e32 v241, 0xffff0000, v181
	v_pk_mul_f32 v[66:67], v[66:67], v[240:241]
	v_lshlrev_b32_e32 v242, 16, v182
	v_and_b32_e32 v243, 0xffff0000, v182
	v_pk_mul_f32 v[68:69], v[68:69], v[242:243]
	v_lshlrev_b32_e32 v234, 16, v183
	v_and_b32_e32 v235, 0xffff0000, v183
	v_pk_mul_f32 v[70:71], v[70:71], v[234:235]
	v_lshlrev_b32_e32 v252, 16, v236
	v_and_b32_e32 v253, 0xffff0000, v236
	v_pk_add_f32 v[64:65], v[64:65], v[252:253]
	v_lshlrev_b32_e32 v178, 16, v237
	v_and_b32_e32 v179, 0xffff0000, v237
	v_pk_add_f32 v[66:67], v[66:67], v[178:179]
	v_lshlrev_b32_e32 v240, 16, v238
	v_and_b32_e32 v241, 0xffff0000, v238
	v_pk_add_f32 v[68:69], v[68:69], v[240:241]
	v_lshlrev_b32_e32 v242, 16, v239
	v_and_b32_e32 v243, 0xffff0000, v239
	v_pk_add_f32 v[70:71], v[70:71], v[242:243]
	v_cvt_pk_bf16_f32 v236, v64, v65
	v_cvt_pk_bf16_f32 v237, v66, v67
	v_cvt_pk_bf16_f32 v238, v68, v69
	v_cvt_pk_bf16_f32 v239, v70, v71
	s_waitcnt vmcnt(8)
	v_lshlrev_b32_e32 v234, 16, v184
	v_and_b32_e32 v235, 0xffff0000, v184
	v_pk_mul_f32 v[72:73], v[72:73], v[234:235]
	v_lshlrev_b32_e32 v252, 16, v185
	v_and_b32_e32 v253, 0xffff0000, v185
	v_pk_mul_f32 v[74:75], v[74:75], v[252:253]
	v_lshlrev_b32_e32 v178, 16, v186
	v_and_b32_e32 v179, 0xffff0000, v186
	v_pk_mul_f32 v[76:77], v[76:77], v[178:179]
	v_lshlrev_b32_e32 v240, 16, v187
	v_and_b32_e32 v241, 0xffff0000, v187
	v_pk_mul_f32 v[78:79], v[78:79], v[240:241]
	v_lshlrev_b32_e32 v242, 16, v244
	v_and_b32_e32 v243, 0xffff0000, v244
	v_pk_add_f32 v[72:73], v[72:73], v[242:243]
	v_lshlrev_b32_e32 v234, 16, v245
	v_and_b32_e32 v235, 0xffff0000, v245
	v_pk_add_f32 v[74:75], v[74:75], v[234:235]
	v_lshlrev_b32_e32 v252, 16, v246
	v_and_b32_e32 v253, 0xffff0000, v246
	v_pk_add_f32 v[76:77], v[76:77], v[252:253]
	v_lshlrev_b32_e32 v178, 16, v247
	v_and_b32_e32 v179, 0xffff0000, v247
	v_pk_add_f32 v[78:79], v[78:79], v[178:179]
	v_cvt_pk_bf16_f32 v244, v72, v73
	v_cvt_pk_bf16_f32 v245, v74, v75
	v_cvt_pk_bf16_f32 v246, v76, v77
	v_cvt_pk_bf16_f32 v247, v78, v79
	s_waitcnt vmcnt(7)
	v_lshlrev_b32_e32 v240, 16, v188
	v_and_b32_e32 v241, 0xffff0000, v188
	v_pk_mul_f32 v[80:81], v[80:81], v[240:241]
	v_lshlrev_b32_e32 v242, 16, v189
	v_and_b32_e32 v243, 0xffff0000, v189
	v_pk_mul_f32 v[82:83], v[82:83], v[242:243]
	v_lshlrev_b32_e32 v234, 16, v190
	v_and_b32_e32 v235, 0xffff0000, v190
	v_pk_mul_f32 v[84:85], v[84:85], v[234:235]
	v_lshlrev_b32_e32 v252, 16, v191
	v_and_b32_e32 v253, 0xffff0000, v191
	v_pk_mul_f32 v[86:87], v[86:87], v[252:253]
	v_lshlrev_b32_e32 v178, 16, v248
	v_and_b32_e32 v179, 0xffff0000, v248
	v_pk_add_f32 v[80:81], v[80:81], v[178:179]
	v_lshlrev_b32_e32 v240, 16, v249
	v_and_b32_e32 v241, 0xffff0000, v249
	v_pk_add_f32 v[82:83], v[82:83], v[240:241]
	v_lshlrev_b32_e32 v242, 16, v250
	v_and_b32_e32 v243, 0xffff0000, v250
	v_pk_add_f32 v[84:85], v[84:85], v[242:243]
	v_lshlrev_b32_e32 v234, 16, v251
	v_and_b32_e32 v235, 0xffff0000, v251
	v_pk_add_f32 v[86:87], v[86:87], v[234:235]
	v_cvt_pk_bf16_f32 v248, v80, v81
	v_cvt_pk_bf16_f32 v249, v82, v83
	v_cvt_pk_bf16_f32 v250, v84, v85
	v_cvt_pk_bf16_f32 v251, v86, v87
	s_waitcnt vmcnt(6)
	s_waitcnt lgkmcnt(0)
	v_lshlrev_b32_e32 v252, 16, v192
	v_and_b32_e32 v253, 0xffff0000, v192
	v_pk_mul_f32 v[88:89], v[88:89], v[252:253]
	v_lshlrev_b32_e32 v178, 16, v193
	v_and_b32_e32 v179, 0xffff0000, v193
	v_pk_mul_f32 v[90:91], v[90:91], v[178:179]
	v_lshlrev_b32_e32 v240, 16, v194
	v_and_b32_e32 v241, 0xffff0000, v194
	v_pk_mul_f32 v[92:93], v[92:93], v[240:241]
	v_lshlrev_b32_e32 v242, 16, v195
	v_and_b32_e32 v243, 0xffff0000, v195
	v_pk_mul_f32 v[94:95], v[94:95], v[242:243]
	v_lshlrev_b32_e32 v234, 16, v196
	v_and_b32_e32 v235, 0xffff0000, v196
	v_pk_add_f32 v[88:89], v[88:89], v[234:235]
	v_lshlrev_b32_e32 v252, 16, v197
	v_and_b32_e32 v253, 0xffff0000, v197
	v_pk_add_f32 v[90:91], v[90:91], v[252:253]
	v_lshlrev_b32_e32 v178, 16, v198
	v_and_b32_e32 v179, 0xffff0000, v198
	v_pk_add_f32 v[92:93], v[92:93], v[178:179]
	v_lshlrev_b32_e32 v240, 16, v199
	v_and_b32_e32 v241, 0xffff0000, v199
	v_pk_add_f32 v[94:95], v[94:95], v[240:241]
	v_cvt_pk_bf16_f32 v192, v88, v89
	v_cvt_pk_bf16_f32 v193, v90, v91
	v_cvt_pk_bf16_f32 v194, v92, v93
	v_cvt_pk_bf16_f32 v195, v94, v95
	ds_write_b128 v177, v[192:195] offset:0
	s_waitcnt lgkmcnt(0)
	s_waitcnt vmcnt(5)
	s_waitcnt lgkmcnt(0)
	v_lshlrev_b32_e32 v242, 16, v0
	v_and_b32_e32 v243, 0xffff0000, v0
	v_pk_mul_f32 v[96:97], v[96:97], v[242:243]
	v_lshlrev_b32_e32 v234, 16, v1
	v_and_b32_e32 v235, 0xffff0000, v1
	v_pk_mul_f32 v[98:99], v[98:99], v[234:235]
	v_lshlrev_b32_e32 v252, 16, v2
	v_and_b32_e32 v253, 0xffff0000, v2
	v_pk_mul_f32 v[100:101], v[100:101], v[252:253]
	v_lshlrev_b32_e32 v178, 16, v3
	v_and_b32_e32 v179, 0xffff0000, v3
	v_pk_mul_f32 v[102:103], v[102:103], v[178:179]
	v_lshlrev_b32_e32 v240, 16, v128
	v_and_b32_e32 v241, 0xffff0000, v128
	v_pk_add_f32 v[96:97], v[96:97], v[240:241]
	v_lshlrev_b32_e32 v242, 16, v129
	v_and_b32_e32 v243, 0xffff0000, v129
	v_pk_add_f32 v[98:99], v[98:99], v[242:243]
	v_lshlrev_b32_e32 v234, 16, v130
	v_and_b32_e32 v235, 0xffff0000, v130
	v_pk_add_f32 v[100:101], v[100:101], v[234:235]
	v_lshlrev_b32_e32 v252, 16, v131
	v_and_b32_e32 v253, 0xffff0000, v131
	v_pk_add_f32 v[102:103], v[102:103], v[252:253]
	v_cvt_pk_bf16_f32 v0, v96, v97
	v_cvt_pk_bf16_f32 v1, v98, v99
	v_cvt_pk_bf16_f32 v2, v100, v101
	v_cvt_pk_bf16_f32 v3, v102, v103
	ds_write_b128 v177, v[0:3] offset:8192
	s_waitcnt lgkmcnt(0)
	s_waitcnt vmcnt(4)
	s_waitcnt lgkmcnt(0)
	v_lshlrev_b32_e32 v178, 16, v4
	v_and_b32_e32 v179, 0xffff0000, v4
	v_pk_mul_f32 v[104:105], v[104:105], v[178:179]
	v_lshlrev_b32_e32 v240, 16, v5
	v_and_b32_e32 v241, 0xffff0000, v5
	v_pk_mul_f32 v[106:107], v[106:107], v[240:241]
	v_lshlrev_b32_e32 v242, 16, v6
	v_and_b32_e32 v243, 0xffff0000, v6
	v_pk_mul_f32 v[108:109], v[108:109], v[242:243]
	v_lshlrev_b32_e32 v234, 16, v7
	v_and_b32_e32 v235, 0xffff0000, v7
	v_pk_mul_f32 v[110:111], v[110:111], v[234:235]
	v_lshlrev_b32_e32 v252, 16, v8
	v_and_b32_e32 v253, 0xffff0000, v8
	v_pk_add_f32 v[104:105], v[104:105], v[252:253]
	v_lshlrev_b32_e32 v178, 16, v9
	v_and_b32_e32 v179, 0xffff0000, v9
	v_pk_add_f32 v[106:107], v[106:107], v[178:179]
	v_lshlrev_b32_e32 v240, 16, v10
	v_and_b32_e32 v241, 0xffff0000, v10
	v_pk_add_f32 v[108:109], v[108:109], v[240:241]
	v_lshlrev_b32_e32 v242, 16, v11
	v_and_b32_e32 v243, 0xffff0000, v11
	v_pk_add_f32 v[110:111], v[110:111], v[242:243]
	v_cvt_pk_bf16_f32 v4, v104, v105
	v_cvt_pk_bf16_f32 v5, v106, v107
	v_cvt_pk_bf16_f32 v6, v108, v109
	v_cvt_pk_bf16_f32 v7, v110, v111
	ds_write_b128 v177, v[4:7] offset:16384
	s_waitcnt lgkmcnt(0)
	s_waitcnt vmcnt(1)
	v_lshlrev_b32_e32 v234, 16, v12
	v_and_b32_e32 v235, 0xffff0000, v12
	v_pk_mul_f32 v[112:113], v[112:113], v[234:235]
	v_lshlrev_b32_e32 v252, 16, v13
	v_and_b32_e32 v253, 0xffff0000, v13
	v_pk_mul_f32 v[114:115], v[114:115], v[252:253]
	v_lshlrev_b32_e32 v178, 16, v14
	v_and_b32_e32 v179, 0xffff0000, v14
	v_pk_mul_f32 v[116:117], v[116:117], v[178:179]
	v_lshlrev_b32_e32 v240, 16, v15
	v_and_b32_e32 v241, 0xffff0000, v15
	v_pk_mul_f32 v[118:119], v[118:119], v[240:241]
	v_lshlrev_b32_e32 v242, 16, v16
	v_and_b32_e32 v243, 0xffff0000, v16
	v_pk_add_f32 v[112:113], v[112:113], v[242:243]
	v_lshlrev_b32_e32 v234, 16, v17
	v_and_b32_e32 v235, 0xffff0000, v17
	v_pk_add_f32 v[114:115], v[114:115], v[234:235]
	v_lshlrev_b32_e32 v252, 16, v18
	v_and_b32_e32 v253, 0xffff0000, v18
	v_pk_add_f32 v[116:117], v[116:117], v[252:253]
	v_lshlrev_b32_e32 v178, 16, v19
	v_and_b32_e32 v179, 0xffff0000, v19
	v_pk_add_f32 v[118:119], v[118:119], v[178:179]
	v_cvt_pk_bf16_f32 v12, v112, v113
	v_cvt_pk_bf16_f32 v13, v114, v115
	v_cvt_pk_bf16_f32 v14, v116, v117
	v_cvt_pk_bf16_f32 v15, v118, v119
	s_mov_b32 s58, 0x58000
	v_lshl_add_u64 v[240:241], v[172:173], 0, s[58:59]
	global_store_dwordx4 v[240:241], v[12:15], off
	s_waitcnt vmcnt(1)
	v_lshlrev_b32_e32 v242, 16, v132
	v_and_b32_e32 v243, 0xffff0000, v132
	v_pk_mul_f32 v[120:121], v[120:121], v[242:243]
	v_lshlrev_b32_e32 v234, 16, v133
	v_and_b32_e32 v235, 0xffff0000, v133
	v_pk_mul_f32 v[122:123], v[122:123], v[234:235]
	v_lshlrev_b32_e32 v252, 16, v134
	v_and_b32_e32 v253, 0xffff0000, v134
	v_pk_mul_f32 v[124:125], v[124:125], v[252:253]
	v_lshlrev_b32_e32 v178, 16, v135
	v_and_b32_e32 v179, 0xffff0000, v135
	v_pk_mul_f32 v[126:127], v[126:127], v[178:179]
	v_lshlrev_b32_e32 v240, 16, v20
	v_and_b32_e32 v241, 0xffff0000, v20
	v_pk_add_f32 v[120:121], v[120:121], v[240:241]
	v_lshlrev_b32_e32 v242, 16, v21
	v_and_b32_e32 v243, 0xffff0000, v21
	v_pk_add_f32 v[122:123], v[122:123], v[242:243]
	v_lshlrev_b32_e32 v234, 16, v22
	v_and_b32_e32 v235, 0xffff0000, v22
	v_pk_add_f32 v[124:125], v[124:125], v[234:235]
	v_lshlrev_b32_e32 v252, 16, v23
	v_and_b32_e32 v253, 0xffff0000, v23
	v_pk_add_f32 v[126:127], v[126:127], v[252:253]
	v_cvt_pk_bf16_f32 v132, v120, v121
	v_cvt_pk_bf16_f32 v133, v122, v123
	v_cvt_pk_bf16_f32 v134, v124, v125
	v_cvt_pk_bf16_f32 v135, v126, v127
	s_mov_b32 s58, 0x58000
	v_lshl_add_u64 v[178:179], v[172:173], 0, s[58:59]
	global_store_dwordx4 v[178:179], v[132:135], off offset:256
	s_branch .Lmepi_done
.Lmepi_z3:
	global_load_dwordx4 v[128:131], v[170:171], off nt
	global_load_dwordx4 v[132:135], v[170:171], off offset:256 nt
	s_mov_b32 s58, 0x20000
	v_lshl_add_u64 v[234:235], v[170:171], 0, s[58:59]
	global_load_dwordx4 v[136:139], v[234:235], off nt
	global_load_dwordx4 v[140:143], v[234:235], off offset:256 nt
	s_mov_b32 s58, 0x40000
	v_lshl_add_u64 v[252:253], v[170:171], 0, s[58:59]
	global_load_dwordx4 v[144:147], v[252:253], off nt
	global_load_dwordx4 v[148:151], v[252:253], off offset:256 nt
	s_mov_b32 s58, 0x60000
	v_lshl_add_u64 v[178:179], v[170:171], 0, s[58:59]
	global_load_dwordx4 v[152:155], v[178:179], off nt
	global_load_dwordx4 v[156:159], v[178:179], off offset:256 nt
	s_mov_b32 s58, 0x100000
	v_lshl_add_u64 v[240:241], v[170:171], 0, s[58:59]
	global_load_dwordx4 v[180:183], v[240:241], off nt
	global_load_dwordx4 v[184:187], v[240:241], off offset:256 nt
	s_mov_b32 s58, 0x120000
	v_lshl_add_u64 v[242:243], v[170:171], 0, s[58:59]
	global_load_dwordx4 v[188:191], v[242:243], off nt
	global_load_dwordx4 v[192:195], v[242:243], off offset:256 nt
	ds_read_b128 v[196:199], v177 offset:0
	s_waitcnt vmcnt(11)
	v_lshlrev_b32_e32 v234, 16, v128
	v_and_b32_e32 v235, 0xffff0000, v128
	v_pk_mul_f32 v[0:1], v[0:1], v[234:235]
	v_lshlrev_b32_e32 v252, 16, v129
	v_and_b32_e32 v253, 0xffff0000, v129
	v_pk_mul_f32 v[2:3], v[2:3], v[252:253]
	v_lshlrev_b32_e32 v178, 16, v130
	v_and_b32_e32 v179, 0xffff0000, v130
	v_pk_mul_f32 v[4:5], v[4:5], v[178:179]
	v_lshlrev_b32_e32 v240, 16, v131
	v_and_b32_e32 v241, 0xffff0000, v131
	v_pk_mul_f32 v[6:7], v[6:7], v[240:241]
	v_lshlrev_b32_e32 v242, 16, v200
	v_and_b32_e32 v243, 0xffff0000, v200
	v_pk_add_f32 v[0:1], v[0:1], v[242:243]
	v_lshlrev_b32_e32 v234, 16, v201
	v_and_b32_e32 v235, 0xffff0000, v201
	v_pk_add_f32 v[2:3], v[2:3], v[234:235]
	v_lshlrev_b32_e32 v252, 16, v202
	v_and_b32_e32 v253, 0xffff0000, v202
	v_pk_add_f32 v[4:5], v[4:5], v[252:253]
	v_lshlrev_b32_e32 v178, 16, v203
	v_and_b32_e32 v179, 0xffff0000, v203
	v_pk_add_f32 v[6:7], v[6:7], v[178:179]
	v_cvt_pk_bf16_f32 v128, v0, v1
	v_cvt_pk_bf16_f32 v129, v2, v3
	v_cvt_pk_bf16_f32 v130, v4, v5
	v_cvt_pk_bf16_f32 v131, v6, v7
	global_store_dwordx4 v[172:173], v[128:131], off sc1
	s_waitcnt vmcnt(11)
	v_lshlrev_b32_e32 v240, 16, v132
	v_and_b32_e32 v241, 0xffff0000, v132
	v_pk_mul_f32 v[8:9], v[8:9], v[240:241]
	v_lshlrev_b32_e32 v242, 16, v133
	v_and_b32_e32 v243, 0xffff0000, v133
	v_pk_mul_f32 v[10:11], v[10:11], v[242:243]
	v_lshlrev_b32_e32 v234, 16, v134
	v_and_b32_e32 v235, 0xffff0000, v134
	v_pk_mul_f32 v[12:13], v[12:13], v[234:235]
	v_lshlrev_b32_e32 v252, 16, v135
	v_and_b32_e32 v253, 0xffff0000, v135
	v_pk_mul_f32 v[14:15], v[14:15], v[252:253]
	v_lshlrev_b32_e32 v178, 16, v204
	v_and_b32_e32 v179, 0xffff0000, v204
	v_pk_add_f32 v[8:9], v[8:9], v[178:179]
	v_lshlrev_b32_e32 v240, 16, v205
	v_and_b32_e32 v241, 0xffff0000, v205
	v_pk_add_f32 v[10:11], v[10:11], v[240:241]
	v_lshlrev_b32_e32 v242, 16, v206
	v_and_b32_e32 v243, 0xffff0000, v206
	v_pk_add_f32 v[12:13], v[12:13], v[242:243]
	v_lshlrev_b32_e32 v234, 16, v207
	v_and_b32_e32 v235, 0xffff0000, v207
	v_pk_add_f32 v[14:15], v[14:15], v[234:235]
	v_cvt_pk_bf16_f32 v132, v8, v9
	v_cvt_pk_bf16_f32 v133, v10, v11
	v_cvt_pk_bf16_f32 v134, v12, v13
	v_cvt_pk_bf16_f32 v135, v14, v15
	global_store_dwordx4 v[172:173], v[132:135], off offset:256 sc1
	s_mov_b32 s58, 0x140000
	v_lshl_add_u64 v[252:253], v[170:171], 0, s[58:59]
	global_load_dwordx4 v[0:3], v[252:253], off nt
	global_load_dwordx4 v[4:7], v[252:253], off offset:256 nt
	ds_read_b128 v[128:131], v177 offset:8192
	ds_read_b128 v[8:11], v177 offset:16384
	s_waitcnt vmcnt(13)
	v_lshlrev_b32_e32 v178, 16, v136
	v_and_b32_e32 v179, 0xffff0000, v136
	v_pk_mul_f32 v[16:17], v[16:17], v[178:179]
	v_lshlrev_b32_e32 v240, 16, v137
	v_and_b32_e32 v241, 0xffff0000, v137
	v_pk_mul_f32 v[18:19], v[18:19], v[240:241]
	v_lshlrev_b32_e32 v242, 16, v138
	v_and_b32_e32 v243, 0xffff0000, v138
	v_pk_mul_f32 v[20:21], v[20:21], v[242:243]
	v_lshlrev_b32_e32 v234, 16, v139
	v_and_b32_e32 v235, 0xffff0000, v139
	v_pk_mul_f32 v[22:23], v[22:23], v[234:235]
	v_lshlrev_b32_e32 v252, 16, v208
	v_and_b32_e32 v253, 0xffff0000, v208
	v_pk_add_f32 v[16:17], v[16:17], v[252:253]
	v_lshlrev_b32_e32 v178, 16, v209
	v_and_b32_e32 v179, 0xffff0000, v209
	v_pk_add_f32 v[18:19], v[18:19], v[178:179]
	v_lshlrev_b32_e32 v240, 16, v210
	v_and_b32_e32 v241, 0xffff0000, v210
	v_pk_add_f32 v[20:21], v[20:21], v[240:241]
	v_lshlrev_b32_e32 v242, 16, v211
	v_and_b32_e32 v243, 0xffff0000, v211
	v_pk_add_f32 v[22:23], v[22:23], v[242:243]
	v_cvt_pk_bf16_f32 v136, v16, v17
	v_cvt_pk_bf16_f32 v137, v18, v19
	v_cvt_pk_bf16_f32 v138, v20, v21
	v_cvt_pk_bf16_f32 v139, v22, v23
	s_mov_b32 s58, 0x8000
	v_lshl_add_u64 v[234:235], v[172:173], 0, s[58:59]
	global_store_dwordx4 v[234:235], v[136:139], off sc1
	s_waitcnt vmcnt(13)
	v_lshlrev_b32_e32 v252, 16, v140
	v_and_b32_e32 v253, 0xffff0000, v140
	v_pk_mul_f32 v[24:25], v[24:25], v[252:253]
	v_lshlrev_b32_e32 v178, 16, v141
	v_and_b32_e32 v179, 0xffff0000, v141
	v_pk_mul_f32 v[26:27], v[26:27], v[178:179]
	v_lshlrev_b32_e32 v240, 16, v142
	v_and_b32_e32 v241, 0xffff0000, v142
	v_pk_mul_f32 v[28:29], v[28:29], v[240:241]
	v_lshlrev_b32_e32 v242, 16, v143
	v_and_b32_e32 v243, 0xffff0000, v143
	v_pk_mul_f32 v[30:31], v[30:31], v[242:243]
	v_lshlrev_b32_e32 v234, 16, v212
	v_and_b32_e32 v235, 0xffff0000, v212
	v_pk_add_f32 v[24:25], v[24:25], v[234:235]
	v_lshlrev_b32_e32 v252, 16, v213
	v_and_b32_e32 v253, 0xffff0000, v213
	v_pk_add_f32 v[26:27], v[26:27], v[252:253]
	v_lshlrev_b32_e32 v178, 16, v214
	v_and_b32_e32 v179, 0xffff0000, v214
	v_pk_add_f32 v[28:29], v[28:29], v[178:179]
	v_lshlrev_b32_e32 v240, 16, v215
	v_and_b32_e32 v241, 0xffff0000, v215
	v_pk_add_f32 v[30:31], v[30:31], v[240:241]
	v_cvt_pk_bf16_f32 v140, v24, v25
	v_cvt_pk_bf16_f32 v141, v26, v27
	v_cvt_pk_bf16_f32 v142, v28, v29
	v_cvt_pk_bf16_f32 v143, v30, v31
	s_mov_b32 s58, 0x8000
	v_lshl_add_u64 v[242:243], v[172:173], 0, s[58:59]
	global_store_dwordx4 v[242:243], v[140:143], off offset:256 sc1
	s_mov_b32 s58, 0x160000
	v_lshl_add_u64 v[234:235], v[170:171], 0, s[58:59]
	global_load_dwordx4 v[12:15], v[234:235], off nt
	global_load_dwordx4 v[132:135], v[234:235], off offset:256 nt
	s_mov_b32 s58, 0x58000
	v_lshl_add_u64 v[252:253], v[172:173], 0, s[58:59]
	global_load_dwordx4 v[16:19], v[252:253], off
	global_load_dwordx4 v[20:23], v[252:253], off offset:256
	s_waitcnt vmcnt(17)
	v_lshlrev_b32_e32 v178, 16, v144
	v_and_b32_e32 v179, 0xffff0000, v144
	v_pk_mul_f32 v[32:33], v[32:33], v[178:179]
	v_lshlrev_b32_e32 v240, 16, v145
	v_and_b32_e32 v241, 0xffff0000, v145
	v_pk_mul_f32 v[34:35], v[34:35], v[240:241]
	v_lshlrev_b32_e32 v242, 16, v146
	v_and_b32_e32 v243, 0xffff0000, v146
	v_pk_mul_f32 v[36:37], v[36:37], v[242:243]
	v_lshlrev_b32_e32 v234, 16, v147
	v_and_b32_e32 v235, 0xffff0000, v147
	v_pk_mul_f32 v[38:39], v[38:39], v[234:235]
	v_lshlrev_b32_e32 v252, 16, v216
	v_and_b32_e32 v253, 0xffff0000, v216
	v_pk_add_f32 v[32:33], v[32:33], v[252:253]
	v_lshlrev_b32_e32 v178, 16, v217
	v_and_b32_e32 v179, 0xffff0000, v217
	v_pk_add_f32 v[34:35], v[34:35], v[178:179]
	v_lshlrev_b32_e32 v240, 16, v218
	v_and_b32_e32 v241, 0xffff0000, v218
	v_pk_add_f32 v[36:37], v[36:37], v[240:241]
	v_lshlrev_b32_e32 v242, 16, v219
	v_and_b32_e32 v243, 0xffff0000, v219
	v_pk_add_f32 v[38:39], v[38:39], v[242:243]
	v_cvt_pk_bf16_f32 v144, v32, v33
	v_cvt_pk_bf16_f32 v145, v34, v35
	v_cvt_pk_bf16_f32 v146, v36, v37
	v_cvt_pk_bf16_f32 v147, v38, v39
	s_mov_b32 s58, 0x10000
	v_lshl_add_u64 v[234:235], v[172:173], 0, s[58:59]
	global_store_dwordx4 v[234:235], v[144:147], off sc1
	s_waitcnt vmcnt(17)
	v_lshlrev_b32_e32 v252, 16, v148
	v_and_b32_e32 v253, 0xffff0000, v148
	v_pk_mul_f32 v[40:41], v[40:41], v[252:253]
	v_lshlrev_b32_e32 v178, 16, v149
	v_and_b32_e32 v179, 0xffff0000, v149
	v_pk_mul_f32 v[42:43], v[42:43], v[178:179]
	v_lshlrev_b32_e32 v240, 16, v150
	v_and_b32_e32 v241, 0xffff0000, v150
	v_pk_mul_f32 v[44:45], v[44:45], v[240:241]
	v_lshlrev_b32_e32 v242, 16, v151
	v_and_b32_e32 v243, 0xffff0000, v151
	v_pk_mul_f32 v[46:47], v[46:47], v[242:243]
	v_lshlrev_b32_e32 v234, 16, v220
	v_and_b32_e32 v235, 0xffff0000, v220
	v_pk_add_f32 v[40:41], v[40:41], v[234:235]
	v_lshlrev_b32_e32 v252, 16, v221
	v_and_b32_e32 v253, 0xffff0000, v221
	v_pk_add_f32 v[42:43], v[42:43], v[252:253]
	v_lshlrev_b32_e32 v178, 16, v222
	v_and_b32_e32 v179, 0xffff0000, v222
	v_pk_add_f32 v[44:45], v[44:45], v[178:179]
	v_lshlrev_b32_e32 v240, 16, v223
	v_and_b32_e32 v241, 0xffff0000, v223
	v_pk_add_f32 v[46:47], v[46:47], v[240:241]
	v_cvt_pk_bf16_f32 v148, v40, v41
	v_cvt_pk_bf16_f32 v149, v42, v43
	v_cvt_pk_bf16_f32 v150, v44, v45
	v_cvt_pk_bf16_f32 v151, v46, v47
	s_mov_b32 s58, 0x10000
	v_lshl_add_u64 v[242:243], v[172:173], 0, s[58:59]
	global_store_dwordx4 v[242:243], v[148:151], off offset:256 sc1
	s_waitcnt vmcnt(17)
	v_lshlrev_b32_e32 v234, 16, v152
	v_and_b32_e32 v235, 0xffff0000, v152
	v_pk_mul_f32 v[48:49], v[48:49], v[234:235]
	v_lshlrev_b32_e32 v252, 16, v153
	v_and_b32_e32 v253, 0xffff0000, v153
	v_pk_mul_f32 v[50:51], v[50:51], v[252:253]
	v_lshlrev_b32_e32 v178, 16, v154
	v_and_b32_e32 v179, 0xffff0000, v154
	v_pk_mul_f32 v[52:53], v[52:53], v[178:179]
	v_lshlrev_b32_e32 v240, 16, v155
	v_and_b32_e32 v241, 0xffff0000, v155
	v_pk_mul_f32 v[54:55], v[54:55], v[240:241]
	v_lshlrev_b32_e32 v242, 16, v224
	v_and_b32_e32 v243, 0xffff0000, v224
	v_pk_add_f32 v[48:49], v[48:49], v[242:243]
	v_lshlrev_b32_e32 v234, 16, v225
	v_and_b32_e32 v235, 0xffff0000, v225
	v_pk_add_f32 v[50:51], v[50:51], v[234:235]
	v_lshlrev_b32_e32 v252, 16, v226
	v_and_b32_e32 v253, 0xffff0000, v226
	v_pk_add_f32 v[52:53], v[52:53], v[252:253]
	v_lshlrev_b32_e32 v178, 16, v227
	v_and_b32_e32 v179, 0xffff0000, v227
	v_pk_add_f32 v[54:55], v[54:55], v[178:179]
	v_cvt_pk_bf16_f32 v152, v48, v49
	v_cvt_pk_bf16_f32 v153, v50, v51
	v_cvt_pk_bf16_f32 v154, v52, v53
	v_cvt_pk_bf16_f32 v155, v54, v55
	s_mov_b32 s58, 0x18000
	v_lshl_add_u64 v[240:241], v[172:173], 0, s[58:59]
	global_store_dwordx4 v[240:241], v[152:155], off sc1
	s_waitcnt vmcnt(17)
	v_lshlrev_b32_e32 v242, 16, v156
	v_and_b32_e32 v243, 0xffff0000, v156
	v_pk_mul_f32 v[56:57], v[56:57], v[242:243]
	v_lshlrev_b32_e32 v234, 16, v157
	v_and_b32_e32 v235, 0xffff0000, v157
	v_pk_mul_f32 v[58:59], v[58:59], v[234:235]
	v_lshlrev_b32_e32 v252, 16, v158
	v_and_b32_e32 v253, 0xffff0000, v158
	v_pk_mul_f32 v[60:61], v[60:61], v[252:253]
	v_lshlrev_b32_e32 v178, 16, v159
	v_and_b32_e32 v179, 0xffff0000, v159
	v_pk_mul_f32 v[62:63], v[62:63], v[178:179]
	v_lshlrev_b32_e32 v240, 16, v228
	v_and_b32_e32 v241, 0xffff0000, v228
	v_pk_add_f32 v[56:57], v[56:57], v[240:241]
	v_lshlrev_b32_e32 v242, 16, v229
	v_and_b32_e32 v243, 0xffff0000, v229
	v_pk_add_f32 v[58:59], v[58:59], v[242:243]
	v_lshlrev_b32_e32 v234, 16, v230
	v_and_b32_e32 v235, 0xffff0000, v230
	v_pk_add_f32 v[60:61], v[60:61], v[234:235]
	v_lshlrev_b32_e32 v252, 16, v231
	v_and_b32_e32 v253, 0xffff0000, v231
	v_pk_add_f32 v[62:63], v[62:63], v[252:253]
	v_cvt_pk_bf16_f32 v156, v56, v57
	v_cvt_pk_bf16_f32 v157, v58, v59
	v_cvt_pk_bf16_f32 v158, v60, v61
	v_cvt_pk_bf16_f32 v159, v62, v63
	s_mov_b32 s58, 0x18000
	v_lshl_add_u64 v[178:179], v[172:173], 0, s[58:59]
	global_store_dwordx4 v[178:179], v[156:159], off offset:256 sc1
	s_waitcnt vmcnt(17)
	v_lshlrev_b32_e32 v240, 16, v180
	v_and_b32_e32 v241, 0xffff0000, v180
	v_pk_mul_f32 v[64:65], v[64:65], v[240:241]
	v_lshlrev_b32_e32 v242, 16, v181
	v_and_b32_e32 v243, 0xffff0000, v181
	v_pk_mul_f32 v[66:67], v[66:67], v[242:243]
	v_lshlrev_b32_e32 v234, 16, v182
	v_and_b32_e32 v235, 0xffff0000, v182
	v_pk_mul_f32 v[68:69], v[68:69], v[234:235]
	v_lshlrev_b32_e32 v252, 16, v183
	v_and_b32_e32 v253, 0xffff0000, v183
	v_pk_mul_f32 v[70:71], v[70:71], v[252:253]
	v_lshlrev_b32_e32 v178, 16, v236
	v_and_b32_e32 v179, 0xffff0000, v236
	v_pk_add_f32 v[64:65], v[64:65], v[178:179]
	v_lshlrev_b32_e32 v240, 16, v237
	v_and_b32_e32 v241, 0xffff0000, v237
	v_pk_add_f32 v[66:67], v[66:67], v[240:241]
	v_lshlrev_b32_e32 v242, 16, v238
	v_and_b32_e32 v243, 0xffff0000, v238
	v_pk_add_f32 v[68:69], v[68:69], v[242:243]
	v_lshlrev_b32_e32 v234, 16, v239
	v_and_b32_e32 v235, 0xffff0000, v239
	v_pk_add_f32 v[70:71], v[70:71], v[234:235]
	v_cvt_pk_bf16_f32 v180, v64, v65
	v_cvt_pk_bf16_f32 v181, v66, v67
	v_cvt_pk_bf16_f32 v182, v68, v69
	v_cvt_pk_bf16_f32 v183, v70, v71
	s_mov_b32 s58, 0x40000
	v_lshl_add_u64 v[252:253], v[172:173], 0, s[58:59]
	global_store_dwordx4 v[252:253], v[180:183], off sc1
	s_waitcnt vmcnt(17)
	v_lshlrev_b32_e32 v178, 16, v184
	v_and_b32_e32 v179, 0xffff0000, v184
	v_pk_mul_f32 v[72:73], v[72:73], v[178:179]
	v_lshlrev_b32_e32 v240, 16, v185
	v_and_b32_e32 v241, 0xffff0000, v185
	v_pk_mul_f32 v[74:75], v[74:75], v[240:241]
	v_lshlrev_b32_e32 v242, 16, v186
	v_and_b32_e32 v243, 0xffff0000, v186
	v_pk_mul_f32 v[76:77], v[76:77], v[242:243]
	v_lshlrev_b32_e32 v234, 16, v187
	v_and_b32_e32 v235, 0xffff0000, v187
	v_pk_mul_f32 v[78:79], v[78:79], v[234:235]
	v_lshlrev_b32_e32 v252, 16, v244
	v_and_b32_e32 v253, 0xffff0000, v244
	v_pk_add_f32 v[72:73], v[72:73], v[252:253]
	v_lshlrev_b32_e32 v178, 16, v245
	v_and_b32_e32 v179, 0xffff0000, v245
	v_pk_add_f32 v[74:75], v[74:75], v[178:179]
	v_lshlrev_b32_e32 v240, 16, v246
	v_and_b32_e32 v241, 0xffff0000, v246
	v_pk_add_f32 v[76:77], v[76:77], v[240:241]
	v_lshlrev_b32_e32 v242, 16, v247
	v_and_b32_e32 v243, 0xffff0000, v247
	v_pk_add_f32 v[78:79], v[78:79], v[242:243]
	v_cvt_pk_bf16_f32 v184, v72, v73
	v_cvt_pk_bf16_f32 v185, v74, v75
	v_cvt_pk_bf16_f32 v186, v76, v77
	v_cvt_pk_bf16_f32 v187, v78, v79
	s_mov_b32 s58, 0x40000
	v_lshl_add_u64 v[234:235], v[172:173], 0, s[58:59]
	global_store_dwordx4 v[234:235], v[184:187], off offset:256 sc1
	s_waitcnt vmcnt(17)
	v_lshlrev_b32_e32 v252, 16, v188
	v_and_b32_e32 v253, 0xffff0000, v188
	v_pk_mul_f32 v[80:81], v[80:81], v[252:253]
	v_lshlrev_b32_e32 v178, 16, v189
	v_and_b32_e32 v179, 0xffff0000, v189
	v_pk_mul_f32 v[82:83], v[82:83], v[178:179]
	v_lshlrev_b32_e32 v240, 16, v190
	v_and_b32_e32 v241, 0xffff0000, v190
	v_pk_mul_f32 v[84:85], v[84:85], v[240:241]
	v_lshlrev_b32_e32 v242, 16, v191
	v_and_b32_e32 v243, 0xffff0000, v191
	v_pk_mul_f32 v[86:87], v[86:87], v[242:243]
	v_lshlrev_b32_e32 v234, 16, v248
	v_and_b32_e32 v235, 0xffff0000, v248
	v_pk_add_f32 v[80:81], v[80:81], v[234:235]
	v_lshlrev_b32_e32 v252, 16, v249
	v_and_b32_e32 v253, 0xffff0000, v249
	v_pk_add_f32 v[82:83], v[82:83], v[252:253]
	v_lshlrev_b32_e32 v178, 16, v250
	v_and_b32_e32 v179, 0xffff0000, v250
	v_pk_add_f32 v[84:85], v[84:85], v[178:179]
	v_lshlrev_b32_e32 v240, 16, v251
	v_and_b32_e32 v241, 0xffff0000, v251
	v_pk_add_f32 v[86:87], v[86:87], v[240:241]
	v_cvt_pk_bf16_f32 v188, v80, v81
	v_cvt_pk_bf16_f32 v189, v82, v83
	v_cvt_pk_bf16_f32 v190, v84, v85
	v_cvt_pk_bf16_f32 v191, v86, v87
	s_mov_b32 s58, 0x48000
	v_lshl_add_u64 v[242:243], v[172:173], 0, s[58:59]
	global_store_dwordx4 v[242:243], v[188:191], off sc1
	s_waitcnt vmcnt(17)
	s_waitcnt lgkmcnt(0)
	v_lshlrev_b32_e32 v234, 16, v192
	v_and_b32_e32 v235, 0xffff0000, v192
	v_pk_mul_f32 v[88:89], v[88:89], v[234:235]
	v_lshlrev_b32_e32 v252, 16, v193
	v_and_b32_e32 v253, 0xffff0000, v193
	v_pk_mul_f32 v[90:91], v[90:91], v[252:253]
	v_lshlrev_b32_e32 v178, 16, v194
	v_and_b32_e32 v179, 0xffff0000, v194
	v_pk_mul_f32 v[92:93], v[92:93], v[178:179]
	v_lshlrev_b32_e32 v240, 16, v195
	v_and_b32_e32 v241, 0xffff0000, v195
	v_pk_mul_f32 v[94:95], v[94:95], v[240:241]
	v_lshlrev_b32_e32 v242, 16, v196
	v_and_b32_e32 v243, 0xffff0000, v196
	v_pk_add_f32 v[88:89], v[88:89], v[242:243]
	v_lshlrev_b32_e32 v234, 16, v197
	v_and_b32_e32 v235, 0xffff0000, v197
	v_pk_add_f32 v[90:91], v[90:91], v[234:235]
	v_lshlrev_b32_e32 v252, 16, v198
	v_and_b32_e32 v253, 0xffff0000, v198
	v_pk_add_f32 v[92:93], v[92:93], v[252:253]
	v_lshlrev_b32_e32 v178, 16, v199
	v_and_b32_e32 v179, 0xffff0000, v199
	v_pk_add_f32 v[94:95], v[94:95], v[178:179]
	v_cvt_pk_bf16_f32 v192, v88, v89
	v_cvt_pk_bf16_f32 v193, v90, v91
	v_cvt_pk_bf16_f32 v194, v92, v93
	v_cvt_pk_bf16_f32 v195, v94, v95
	s_mov_b32 s58, 0x48000
	v_lshl_add_u64 v[240:241], v[172:173], 0, s[58:59]
	global_store_dwordx4 v[240:241], v[192:195], off offset:256 sc1
	s_waitcnt vmcnt(15)
	s_waitcnt lgkmcnt(0)
	v_lshlrev_b32_e32 v242, 16, v0
	v_and_b32_e32 v243, 0xffff0000, v0
	v_pk_mul_f32 v[96:97], v[96:97], v[242:243]
	v_lshlrev_b32_e32 v234, 16, v1
	v_and_b32_e32 v235, 0xffff0000, v1
	v_pk_mul_f32 v[98:99], v[98:99], v[234:235]
	v_lshlrev_b32_e32 v252, 16, v2
	v_and_b32_e32 v253, 0xffff0000, v2
	v_pk_mul_f32 v[100:101], v[100:101], v[252:253]
	v_lshlrev_b32_e32 v178, 16, v3
	v_and_b32_e32 v179, 0xffff0000, v3
	v_pk_mul_f32 v[102:103], v[102:103], v[178:179]
	v_lshlrev_b32_e32 v240, 16, v128
	v_and_b32_e32 v241, 0xffff0000, v128
	v_pk_add_f32 v[96:97], v[96:97], v[240:241]
	v_lshlrev_b32_e32 v242, 16, v129
	v_and_b32_e32 v243, 0xffff0000, v129
	v_pk_add_f32 v[98:99], v[98:99], v[242:243]
	v_lshlrev_b32_e32 v234, 16, v130
	v_and_b32_e32 v235, 0xffff0000, v130
	v_pk_add_f32 v[100:101], v[100:101], v[234:235]
	v_lshlrev_b32_e32 v252, 16, v131
	v_and_b32_e32 v253, 0xffff0000, v131
	v_pk_add_f32 v[102:103], v[102:103], v[252:253]
	v_cvt_pk_bf16_f32 v0, v96, v97
	v_cvt_pk_bf16_f32 v1, v98, v99
	v_cvt_pk_bf16_f32 v2, v100, v101
	v_cvt_pk_bf16_f32 v3, v102, v103
	s_mov_b32 s58, 0x50000
	v_lshl_add_u64 v[178:179], v[172:173], 0, s[58:59]
	global_store_dwordx4 v[178:179], v[0:3], off sc1
	s_waitcnt vmcnt(15)
	s_waitcnt lgkmcnt(0)
	v_lshlrev_b32_e32 v240, 16, v4
	v_and_b32_e32 v241, 0xffff0000, v4
	v_pk_mul_f32 v[104:105], v[104:105], v[240:241]
	v_lshlrev_b32_e32 v242, 16, v5
	v_and_b32_e32 v243, 0xffff0000, v5
	v_pk_mul_f32 v[106:107], v[106:107], v[242:243]
	v_lshlrev_b32_e32 v234, 16, v6
	v_and_b32_e32 v235, 0xffff0000, v6
	v_pk_mul_f32 v[108:109], v[108:109], v[234:235]
	v_lshlrev_b32_e32 v252, 16, v7
	v_and_b32_e32 v253, 0xffff0000, v7
	v_pk_mul_f32 v[110:111], v[110:111], v[252:253]
	v_lshlrev_b32_e32 v178, 16, v8
	v_and_b32_e32 v179, 0xffff0000, v8
	v_pk_add_f32 v[104:105], v[104:105], v[178:179]
	v_lshlrev_b32_e32 v240, 16, v9
	v_and_b32_e32 v241, 0xffff0000, v9
	v_pk_add_f32 v[106:107], v[106:107], v[240:241]
	v_lshlrev_b32_e32 v242, 16, v10
	v_and_b32_e32 v243, 0xffff0000, v10
	v_pk_add_f32 v[108:109], v[108:109], v[242:243]
	v_lshlrev_b32_e32 v234, 16, v11
	v_and_b32_e32 v235, 0xffff0000, v11
	v_pk_add_f32 v[110:111], v[110:111], v[234:235]
	v_cvt_pk_bf16_f32 v4, v104, v105
	v_cvt_pk_bf16_f32 v5, v106, v107
	v_cvt_pk_bf16_f32 v6, v108, v109
	v_cvt_pk_bf16_f32 v7, v110, v111
	s_mov_b32 s58, 0x50000
	v_lshl_add_u64 v[252:253], v[172:173], 0, s[58:59]
	global_store_dwordx4 v[252:253], v[4:7], off offset:256 sc1
	s_waitcnt vmcnt(11)
	v_lshlrev_b32_e32 v178, 16, v12
	v_and_b32_e32 v179, 0xffff0000, v12
	v_pk_mul_f32 v[112:113], v[112:113], v[178:179]
	v_lshlrev_b32_e32 v240, 16, v13
	v_and_b32_e32 v241, 0xffff0000, v13
	v_pk_mul_f32 v[114:115], v[114:115], v[240:241]
	v_lshlrev_b32_e32 v242, 16, v14
	v_and_b32_e32 v243, 0xffff0000, v14
	v_pk_mul_f32 v[116:117], v[116:117], v[242:243]
	v_lshlrev_b32_e32 v234, 16, v15
	v_and_b32_e32 v235, 0xffff0000, v15
	v_pk_mul_f32 v[118:119], v[118:119], v[234:235]
	v_lshlrev_b32_e32 v252, 16, v16
	v_and_b32_e32 v253, 0xffff0000, v16
	v_pk_add_f32 v[112:113], v[112:113], v[252:253]
	v_lshlrev_b32_e32 v178, 16, v17
	v_and_b32_e32 v179, 0xffff0000, v17
	v_pk_add_f32 v[114:115], v[114:115], v[178:179]
	v_lshlrev_b32_e32 v240, 16, v18
	v_and_b32_e32 v241, 0xffff0000, v18
	v_pk_add_f32 v[116:117], v[116:117], v[240:241]
	v_lshlrev_b32_e32 v242, 16, v19
	v_and_b32_e32 v243, 0xffff0000, v19
	v_pk_add_f32 v[118:119], v[118:119], v[242:243]
	v_cvt_pk_bf16_f32 v12, v112, v113
	v_cvt_pk_bf16_f32 v13, v114, v115
	v_cvt_pk_bf16_f32 v14, v116, v117
	v_cvt_pk_bf16_f32 v15, v118, v119
	s_mov_b32 s58, 0x58000
	v_lshl_add_u64 v[234:235], v[172:173], 0, s[58:59]
	global_store_dwordx4 v[234:235], v[12:15], off sc1
	s_waitcnt vmcnt(11)
	v_lshlrev_b32_e32 v252, 16, v132
	v_and_b32_e32 v253, 0xffff0000, v132
	v_pk_mul_f32 v[120:121], v[120:121], v[252:253]
	v_lshlrev_b32_e32 v178, 16, v133
	v_and_b32_e32 v179, 0xffff0000, v133
	v_pk_mul_f32 v[122:123], v[122:123], v[178:179]
	v_lshlrev_b32_e32 v240, 16, v134
	v_and_b32_e32 v241, 0xffff0000, v134
	v_pk_mul_f32 v[124:125], v[124:125], v[240:241]
	v_lshlrev_b32_e32 v242, 16, v135
	v_and_b32_e32 v243, 0xffff0000, v135
	v_pk_mul_f32 v[126:127], v[126:127], v[242:243]
	v_lshlrev_b32_e32 v234, 16, v20
	v_and_b32_e32 v235, 0xffff0000, v20
	v_pk_add_f32 v[120:121], v[120:121], v[234:235]
	v_lshlrev_b32_e32 v252, 16, v21
	v_and_b32_e32 v253, 0xffff0000, v21
	v_pk_add_f32 v[122:123], v[122:123], v[252:253]
	v_lshlrev_b32_e32 v178, 16, v22
	v_and_b32_e32 v179, 0xffff0000, v22
	v_pk_add_f32 v[124:125], v[124:125], v[178:179]
	v_lshlrev_b32_e32 v240, 16, v23
	v_and_b32_e32 v241, 0xffff0000, v23
	v_pk_add_f32 v[126:127], v[126:127], v[240:241]
	v_cvt_pk_bf16_f32 v132, v120, v121
	v_cvt_pk_bf16_f32 v133, v122, v123
	v_cvt_pk_bf16_f32 v134, v124, v125
	v_cvt_pk_bf16_f32 v135, v126, v127
	s_mov_b32 s58, 0x58000
	v_lshl_add_u64 v[242:243], v[172:173], 0, s[58:59]
	global_store_dwordx4 v[242:243], v[132:135], off offset:256 sc1
	s_branch .Lmepi_done
.Lmepi_z0:
	global_load_dwordx4 v[128:131], v[170:171], off nt
	global_load_dwordx4 v[132:135], v[170:171], off offset:256 nt
	s_mov_b32 s58, 0x20000
	v_lshl_add_u64 v[234:235], v[170:171], 0, s[58:59]
	global_load_dwordx4 v[136:139], v[234:235], off nt
	global_load_dwordx4 v[140:143], v[234:235], off offset:256 nt
	s_mov_b32 s58, 0x40000
	v_lshl_add_u64 v[252:253], v[170:171], 0, s[58:59]
	global_load_dwordx4 v[144:147], v[252:253], off nt
	global_load_dwordx4 v[148:151], v[252:253], off offset:256 nt
	s_mov_b32 s58, 0x60000
	v_lshl_add_u64 v[178:179], v[170:171], 0, s[58:59]
	global_load_dwordx4 v[152:155], v[178:179], off nt
	global_load_dwordx4 v[156:159], v[178:179], off offset:256 nt
	s_mov_b32 s58, 0x100000
	v_lshl_add_u64 v[240:241], v[170:171], 0, s[58:59]
	global_load_dwordx4 v[180:183], v[240:241], off nt
	global_load_dwordx4 v[184:187], v[240:241], off offset:256 nt
	s_mov_b32 s58, 0x120000
	v_lshl_add_u64 v[242:243], v[170:171], 0, s[58:59]
	global_load_dwordx4 v[188:191], v[242:243], off nt
	global_load_dwordx4 v[192:195], v[242:243], off offset:256 nt
	s_waitcnt vmcnt(11)
	v_lshlrev_b32_e32 v234, 16, v128
	v_and_b32_e32 v235, 0xffff0000, v128
	v_pk_mul_f32 v[0:1], v[0:1], v[234:235]
	v_lshlrev_b32_e32 v252, 16, v129
	v_and_b32_e32 v253, 0xffff0000, v129
	v_pk_mul_f32 v[2:3], v[2:3], v[252:253]
	v_lshlrev_b32_e32 v178, 16, v130
	v_and_b32_e32 v179, 0xffff0000, v130
	v_pk_mul_f32 v[4:5], v[4:5], v[178:179]
	v_lshlrev_b32_e32 v240, 16, v131
	v_and_b32_e32 v241, 0xffff0000, v131
	v_pk_mul_f32 v[6:7], v[6:7], v[240:241]
	v_cvt_pk_bf16_f32 v200, v0, v1
	v_cvt_pk_bf16_f32 v201, v2, v3
	v_cvt_pk_bf16_f32 v202, v4, v5
	v_cvt_pk_bf16_f32 v203, v6, v7
	s_waitcnt vmcnt(10)
	v_lshlrev_b32_e32 v242, 16, v132
	v_and_b32_e32 v243, 0xffff0000, v132
	v_pk_mul_f32 v[8:9], v[8:9], v[242:243]
	v_lshlrev_b32_e32 v234, 16, v133
	v_and_b32_e32 v235, 0xffff0000, v133
	v_pk_mul_f32 v[10:11], v[10:11], v[234:235]
	v_lshlrev_b32_e32 v252, 16, v134
	v_and_b32_e32 v253, 0xffff0000, v134
	v_pk_mul_f32 v[12:13], v[12:13], v[252:253]
	v_lshlrev_b32_e32 v178, 16, v135
	v_and_b32_e32 v179, 0xffff0000, v135
	v_pk_mul_f32 v[14:15], v[14:15], v[178:179]
	v_cvt_pk_bf16_f32 v204, v8, v9
	v_cvt_pk_bf16_f32 v205, v10, v11
	v_cvt_pk_bf16_f32 v206, v12, v13
	v_cvt_pk_bf16_f32 v207, v14, v15
	s_mov_b32 s58, 0x140000
	v_lshl_add_u64 v[240:241], v[170:171], 0, s[58:59]
	global_load_dwordx4 v[196:199], v[240:241], off nt
	global_load_dwordx4 v[0:3], v[240:241], off offset:256 nt
	s_mov_b32 s58, 0x160000
	v_lshl_add_u64 v[242:243], v[170:171], 0, s[58:59]
	global_load_dwordx4 v[4:7], v[242:243], off nt
	global_load_dwordx4 v[128:131], v[242:243], off offset:256 nt
	s_waitcnt vmcnt(13)
	v_lshlrev_b32_e32 v234, 16, v136
	v_and_b32_e32 v235, 0xffff0000, v136
	v_pk_mul_f32 v[16:17], v[16:17], v[234:235]
	v_lshlrev_b32_e32 v252, 16, v137
	v_and_b32_e32 v253, 0xffff0000, v137
	v_pk_mul_f32 v[18:19], v[18:19], v[252:253]
	v_lshlrev_b32_e32 v178, 16, v138
	v_and_b32_e32 v179, 0xffff0000, v138
	v_pk_mul_f32 v[20:21], v[20:21], v[178:179]
	v_lshlrev_b32_e32 v240, 16, v139
	v_and_b32_e32 v241, 0xffff0000, v139
	v_pk_mul_f32 v[22:23], v[22:23], v[240:241]
	v_cvt_pk_bf16_f32 v208, v16, v17
	v_cvt_pk_bf16_f32 v209, v18, v19
	v_cvt_pk_bf16_f32 v210, v20, v21
	v_cvt_pk_bf16_f32 v211, v22, v23
	s_waitcnt vmcnt(12)
	v_lshlrev_b32_e32 v242, 16, v140
	v_and_b32_e32 v243, 0xffff0000, v140
	v_pk_mul_f32 v[24:25], v[24:25], v[242:243]
	v_lshlrev_b32_e32 v234, 16, v141
	v_and_b32_e32 v235, 0xffff0000, v141
	v_pk_mul_f32 v[26:27], v[26:27], v[234:235]
	v_lshlrev_b32_e32 v252, 16, v142
	v_and_b32_e32 v253, 0xffff0000, v142
	v_pk_mul_f32 v[28:29], v[28:29], v[252:253]
	v_lshlrev_b32_e32 v178, 16, v143
	v_and_b32_e32 v179, 0xffff0000, v143
	v_pk_mul_f32 v[30:31], v[30:31], v[178:179]
	v_cvt_pk_bf16_f32 v212, v24, v25
	v_cvt_pk_bf16_f32 v213, v26, v27
	v_cvt_pk_bf16_f32 v214, v28, v29
	v_cvt_pk_bf16_f32 v215, v30, v31
	s_waitcnt vmcnt(11)
	v_lshlrev_b32_e32 v240, 16, v144
	v_and_b32_e32 v241, 0xffff0000, v144
	v_pk_mul_f32 v[32:33], v[32:33], v[240:241]
	v_lshlrev_b32_e32 v242, 16, v145
	v_and_b32_e32 v243, 0xffff0000, v145
	v_pk_mul_f32 v[34:35], v[34:35], v[242:243]
	v_lshlrev_b32_e32 v234, 16, v146
	v_and_b32_e32 v235, 0xffff0000, v146
	v_pk_mul_f32 v[36:37], v[36:37], v[234:235]
	v_lshlrev_b32_e32 v252, 16, v147
	v_and_b32_e32 v253, 0xffff0000, v147
	v_pk_mul_f32 v[38:39], v[38:39], v[252:253]
	v_cvt_pk_bf16_f32 v216, v32, v33
	v_cvt_pk_bf16_f32 v217, v34, v35
	v_cvt_pk_bf16_f32 v218, v36, v37
	v_cvt_pk_bf16_f32 v219, v38, v39
	s_waitcnt vmcnt(10)
	v_lshlrev_b32_e32 v178, 16, v148
	v_and_b32_e32 v179, 0xffff0000, v148
	v_pk_mul_f32 v[40:41], v[40:41], v[178:179]
	v_lshlrev_b32_e32 v240, 16, v149
	v_and_b32_e32 v241, 0xffff0000, v149
	v_pk_mul_f32 v[42:43], v[42:43], v[240:241]
	v_lshlrev_b32_e32 v242, 16, v150
	v_and_b32_e32 v243, 0xffff0000, v150
	v_pk_mul_f32 v[44:45], v[44:45], v[242:243]
	v_lshlrev_b32_e32 v234, 16, v151
	v_and_b32_e32 v235, 0xffff0000, v151
	v_pk_mul_f32 v[46:47], v[46:47], v[234:235]
	v_cvt_pk_bf16_f32 v220, v40, v41
	v_cvt_pk_bf16_f32 v221, v42, v43
	v_cvt_pk_bf16_f32 v222, v44, v45
	v_cvt_pk_bf16_f32 v223, v46, v47
	s_waitcnt vmcnt(9)
	v_lshlrev_b32_e32 v252, 16, v152
	v_and_b32_e32 v253, 0xffff0000, v152
	v_pk_mul_f32 v[48:49], v[48:49], v[252:253]
	v_lshlrev_b32_e32 v178, 16, v153
	v_and_b32_e32 v179, 0xffff0000, v153
	v_pk_mul_f32 v[50:51], v[50:51], v[178:179]
	v_lshlrev_b32_e32 v240, 16, v154
	v_and_b32_e32 v241, 0xffff0000, v154
	v_pk_mul_f32 v[52:53], v[52:53], v[240:241]
	v_lshlrev_b32_e32 v242, 16, v155
	v_and_b32_e32 v243, 0xffff0000, v155
	v_pk_mul_f32 v[54:55], v[54:55], v[242:243]
	v_cvt_pk_bf16_f32 v224, v48, v49
	v_cvt_pk_bf16_f32 v225, v50, v51
	v_cvt_pk_bf16_f32 v226, v52, v53
	v_cvt_pk_bf16_f32 v227, v54, v55
	s_waitcnt vmcnt(8)
	v_lshlrev_b32_e32 v234, 16, v156
	v_and_b32_e32 v235, 0xffff0000, v156
	v_pk_mul_f32 v[56:57], v[56:57], v[234:235]
	v_lshlrev_b32_e32 v252, 16, v157
	v_and_b32_e32 v253, 0xffff0000, v157
	v_pk_mul_f32 v[58:59], v[58:59], v[252:253]
	v_lshlrev_b32_e32 v178, 16, v158
	v_and_b32_e32 v179, 0xffff0000, v158
	v_pk_mul_f32 v[60:61], v[60:61], v[178:179]
	v_lshlrev_b32_e32 v240, 16, v159
	v_and_b32_e32 v241, 0xffff0000, v159
	v_pk_mul_f32 v[62:63], v[62:63], v[240:241]
	v_cvt_pk_bf16_f32 v228, v56, v57
	v_cvt_pk_bf16_f32 v229, v58, v59
	v_cvt_pk_bf16_f32 v230, v60, v61
	v_cvt_pk_bf16_f32 v231, v62, v63
	s_waitcnt vmcnt(7)
	v_lshlrev_b32_e32 v242, 16, v180
	v_and_b32_e32 v243, 0xffff0000, v180
	v_pk_mul_f32 v[64:65], v[64:65], v[242:243]
	v_lshlrev_b32_e32 v234, 16, v181
	v_and_b32_e32 v235, 0xffff0000, v181
	v_pk_mul_f32 v[66:67], v[66:67], v[234:235]
	v_lshlrev_b32_e32 v252, 16, v182
	v_and_b32_e32 v253, 0xffff0000, v182
	v_pk_mul_f32 v[68:69], v[68:69], v[252:253]
	v_lshlrev_b32_e32 v178, 16, v183
	v_and_b32_e32 v179, 0xffff0000, v183
	v_pk_mul_f32 v[70:71], v[70:71], v[178:179]
	v_cvt_pk_bf16_f32 v236, v64, v65
	v_cvt_pk_bf16_f32 v237, v66, v67
	v_cvt_pk_bf16_f32 v238, v68, v69
	v_cvt_pk_bf16_f32 v239, v70, v71
	s_waitcnt vmcnt(6)
	v_lshlrev_b32_e32 v240, 16, v184
	v_and_b32_e32 v241, 0xffff0000, v184
	v_pk_mul_f32 v[72:73], v[72:73], v[240:241]
	v_lshlrev_b32_e32 v242, 16, v185
	v_and_b32_e32 v243, 0xffff0000, v185
	v_pk_mul_f32 v[74:75], v[74:75], v[242:243]
	v_lshlrev_b32_e32 v234, 16, v186
	v_and_b32_e32 v235, 0xffff0000, v186
	v_pk_mul_f32 v[76:77], v[76:77], v[234:235]
	v_lshlrev_b32_e32 v252, 16, v187
	v_and_b32_e32 v253, 0xffff0000, v187
	v_pk_mul_f32 v[78:79], v[78:79], v[252:253]
	v_cvt_pk_bf16_f32 v244, v72, v73
	v_cvt_pk_bf16_f32 v245, v74, v75
	v_cvt_pk_bf16_f32 v246, v76, v77
	v_cvt_pk_bf16_f32 v247, v78, v79
	s_waitcnt vmcnt(5)
	v_lshlrev_b32_e32 v178, 16, v188
	v_and_b32_e32 v179, 0xffff0000, v188
	v_pk_mul_f32 v[80:81], v[80:81], v[178:179]
	v_lshlrev_b32_e32 v240, 16, v189
	v_and_b32_e32 v241, 0xffff0000, v189
	v_pk_mul_f32 v[82:83], v[82:83], v[240:241]
	v_lshlrev_b32_e32 v242, 16, v190
	v_and_b32_e32 v243, 0xffff0000, v190
	v_pk_mul_f32 v[84:85], v[84:85], v[242:243]
	v_lshlrev_b32_e32 v234, 16, v191
	v_and_b32_e32 v235, 0xffff0000, v191
	v_pk_mul_f32 v[86:87], v[86:87], v[234:235]
	v_cvt_pk_bf16_f32 v248, v80, v81
	v_cvt_pk_bf16_f32 v249, v82, v83
	v_cvt_pk_bf16_f32 v250, v84, v85
	v_cvt_pk_bf16_f32 v251, v86, v87
	s_waitcnt vmcnt(4)
	v_lshlrev_b32_e32 v252, 16, v192
	v_and_b32_e32 v253, 0xffff0000, v192
	v_pk_mul_f32 v[88:89], v[88:89], v[252:253]
	v_lshlrev_b32_e32 v178, 16, v193
	v_and_b32_e32 v179, 0xffff0000, v193
	v_pk_mul_f32 v[90:91], v[90:91], v[178:179]
	v_lshlrev_b32_e32 v240, 16, v194
	v_and_b32_e32 v241, 0xffff0000, v194
	v_pk_mul_f32 v[92:93], v[92:93], v[240:241]
	v_lshlrev_b32_e32 v242, 16, v195
	v_and_b32_e32 v243, 0xffff0000, v195
	v_pk_mul_f32 v[94:95], v[94:95], v[242:243]
	v_cvt_pk_bf16_f32 v192, v88, v89
	v_cvt_pk_bf16_f32 v193, v90, v91
	v_cvt_pk_bf16_f32 v194, v92, v93
	v_cvt_pk_bf16_f32 v195, v94, v95
	ds_write_b128 v177, v[192:195] offset:0
	s_waitcnt lgkmcnt(0)
	s_waitcnt vmcnt(3)
	v_lshlrev_b32_e32 v234, 16, v196
	v_and_b32_e32 v235, 0xffff0000, v196
	v_pk_mul_f32 v[96:97], v[96:97], v[234:235]
	v_lshlrev_b32_e32 v252, 16, v197
	v_and_b32_e32 v253, 0xffff0000, v197
	v_pk_mul_f32 v[98:99], v[98:99], v[252:253]
	v_lshlrev_b32_e32 v178, 16, v198
	v_and_b32_e32 v179, 0xffff0000, v198
	v_pk_mul_f32 v[100:101], v[100:101], v[178:179]
	v_lshlrev_b32_e32 v240, 16, v199
	v_and_b32_e32 v241, 0xffff0000, v199
	v_pk_mul_f32 v[102:103], v[102:103], v[240:241]
	v_cvt_pk_bf16_f32 v196, v96, v97
	v_cvt_pk_bf16_f32 v197, v98, v99
	v_cvt_pk_bf16_f32 v198, v100, v101
	v_cvt_pk_bf16_f32 v199, v102, v103
	ds_write_b128 v177, v[196:199] offset:8192
	s_waitcnt lgkmcnt(0)
	s_waitcnt vmcnt(2)
	v_lshlrev_b32_e32 v242, 16, v0
	v_and_b32_e32 v243, 0xffff0000, v0
	v_pk_mul_f32 v[104:105], v[104:105], v[242:243]
	v_lshlrev_b32_e32 v234, 16, v1
	v_and_b32_e32 v235, 0xffff0000, v1
	v_pk_mul_f32 v[106:107], v[106:107], v[234:235]
	v_lshlrev_b32_e32 v252, 16, v2
	v_and_b32_e32 v253, 0xffff0000, v2
	v_pk_mul_f32 v[108:109], v[108:109], v[252:253]
	v_lshlrev_b32_e32 v178, 16, v3
	v_and_b32_e32 v179, 0xffff0000, v3
	v_pk_mul_f32 v[110:111], v[110:111], v[178:179]
	v_cvt_pk_bf16_f32 v0, v104, v105
	v_cvt_pk_bf16_f32 v1, v106, v107
	v_cvt_pk_bf16_f32 v2, v108, v109
	v_cvt_pk_bf16_f32 v3, v110, v111
	ds_write_b128 v177, v[0:3] offset:16384
	s_waitcnt lgkmcnt(0)
	s_waitcnt vmcnt(1)
	v_lshlrev_b32_e32 v240, 16, v4
	v_and_b32_e32 v241, 0xffff0000, v4
	v_pk_mul_f32 v[112:113], v[112:113], v[240:241]
	v_lshlrev_b32_e32 v242, 16, v5
	v_and_b32_e32 v243, 0xffff0000, v5
	v_pk_mul_f32 v[114:115], v[114:115], v[242:243]
	v_lshlrev_b32_e32 v234, 16, v6
	v_and_b32_e32 v235, 0xffff0000, v6
	v_pk_mul_f32 v[116:117], v[116:117], v[234:235]
	v_lshlrev_b32_e32 v252, 16, v7
	v_and_b32_e32 v253, 0xffff0000, v7
	v_pk_mul_f32 v[118:119], v[118:119], v[252:253]
	v_cvt_pk_bf16_f32 v4, v112, v113
	v_cvt_pk_bf16_f32 v5, v114, v115
	v_cvt_pk_bf16_f32 v6, v116, v117
	v_cvt_pk_bf16_f32 v7, v118, v119
	s_mov_b32 s58, 0x58000
	v_lshl_add_u64 v[178:179], v[172:173], 0, s[58:59]
	global_store_dwordx4 v[178:179], v[4:7], off
	s_waitcnt vmcnt(1)
	v_lshlrev_b32_e32 v240, 16, v128
	v_and_b32_e32 v241, 0xffff0000, v128
	v_pk_mul_f32 v[120:121], v[120:121], v[240:241]
	v_lshlrev_b32_e32 v242, 16, v129
	v_and_b32_e32 v243, 0xffff0000, v129
	v_pk_mul_f32 v[122:123], v[122:123], v[242:243]
	v_lshlrev_b32_e32 v234, 16, v130
	v_and_b32_e32 v235, 0xffff0000, v130
	v_pk_mul_f32 v[124:125], v[124:125], v[234:235]
	v_lshlrev_b32_e32 v252, 16, v131
	v_and_b32_e32 v253, 0xffff0000, v131
	v_pk_mul_f32 v[126:127], v[126:127], v[252:253]
	v_cvt_pk_bf16_f32 v128, v120, v121
	v_cvt_pk_bf16_f32 v129, v122, v123
	v_cvt_pk_bf16_f32 v130, v124, v125
	v_cvt_pk_bf16_f32 v131, v126, v127
	s_mov_b32 s58, 0x58000
	v_lshl_add_u64 v[178:179], v[172:173], 0, s[58:59]
	global_store_dwordx4 v[178:179], v[128:131], off offset:256

.LBB0_1087:
	v_mov_b32_e32 v230, 0xff
	v_mov_b32_e32 v231, 0x0
	v_mov_b32_e32 v243, 0x3727c5ac
	v_mov_b32_e32 v248, 0x260
	v_mov_b32_e32 v249, 0x358637bd
	v_mov_b32_e32 v250, 0xff
	v_mov_b32_e32 v251, 0x1c000
	s_waitcnt vmcnt(0)
	s_movk_i32 s46, 0xe800
	s_barrier
